# speedup vs baseline: 1.0033x; 1.0001x over previous
.LBB0_377:
	s_add_u32 s3, s16, 0xfff80080
	s_addc_u32 s18, s17, -1
	s_add_i32 s42, 0, 0x10000
	s_cmp_eq_u32 s41, 28
	s_cselect_b32 s21, s11, s18
	s_cselect_b32 s20, s31, s3
	v_add_u32_e32 v152, s42, v155
	s_cselect_b32 s19, s9, s40
	s_cselect_b32 s18, s34, s35
	s_add_i32 s3, 0, 0x14000
	ds_read_b128 v[140:143], v152
	ds_read_b128 v[144:147], v152 offset:1024
	ds_read_b128 v[148:151], v152 offset:2048
	ds_read_b128 v[158:161], v152 offset:3072
	v_add_u32_e32 v152, s3, v155
	ds_read_b128 v[162:165], v152
	ds_read_b128 v[166:169], v152 offset:1024
	ds_read_b128 v[170:173], v152 offset:2048
	ds_read_b128 v[174:177], v152 offset:3072
	v_lshl_add_u64 v[152:153], s[16:17], 0, v[136:137]
	s_add_i32 m0, s22, 0xc000
	ds_read_b128 v[188:191], v157
	ds_read_b128 v[192:195], v157 offset:1024
	ds_read_b128 v[196:199], v157 offset:2048
	ds_read_b128 v[200:203], v157 offset:3072
	ds_read_b128 v[204:207], v157 offset:4096
	ds_read_b128 v[218:221], v157 offset:5120
	ds_read_b128 v[222:225], v157 offset:6144
	ds_read_b128 v[226:229], v157 offset:7168
	global_load_lds_dwordx4 v[152:153], off
	v_lshl_add_u64 v[152:153], s[16:17], 0, v[138:139]
	s_add_i32 m0, s22, 0xe000
	s_nop 0
	global_load_lds_dwordx4 v[152:153], off
	s_waitcnt vmcnt(8)
	s_waitcnt lgkmcnt(0)
	v_mfma_f32_16x16x32_bf16 v[126:129], v[140:143], v[188:191], v[126:129]
	v_mfma_f32_16x16x32_bf16 v[122:125], v[148:151], v[188:191], v[122:125]
	s_barrier
	s_setprio 1
	v_mfma_f32_16x16x32_bf16 v[110:113], v[140:143], v[196:199], v[110:113]
	v_mfma_f32_16x16x32_bf16 v[106:109], v[148:151], v[196:199], v[106:109]
	v_mfma_f32_16x16x32_bf16 v[94:97], v[140:143], v[204:207], v[94:97]
	v_mfma_f32_16x16x32_bf16 v[90:93], v[148:151], v[204:207], v[90:93]
	v_mfma_f32_16x16x32_bf16 v[78:81], v[140:143], v[222:225], v[78:81]
	v_mfma_f32_16x16x32_bf16 v[74:77], v[148:151], v[222:225], v[74:77]
	v_mfma_f32_16x16x32_bf16 v[126:129], v[144:147], v[192:195], v[126:129]
	v_mfma_f32_16x16x32_bf16 v[122:125], v[158:161], v[192:195], v[122:125]
	v_mfma_f32_16x16x32_bf16 v[110:113], v[144:147], v[200:203], v[110:113]
	v_mfma_f32_16x16x32_bf16 v[106:109], v[158:161], v[200:203], v[106:109]
	v_mfma_f32_16x16x32_bf16 v[94:97], v[144:147], v[218:221], v[94:97]
	v_mfma_f32_16x16x32_bf16 v[90:93], v[158:161], v[218:221], v[90:93]
	v_mfma_f32_16x16x32_bf16 v[78:81], v[144:147], v[226:229], v[78:81]
	v_mfma_f32_16x16x32_bf16 v[74:77], v[158:161], v[226:229], v[74:77]
	s_setprio 0
	s_setprio 1
	v_mfma_f32_16x16x32_bf16 v[118:121], v[162:165], v[188:191], v[118:121]
	v_mfma_f32_16x16x32_bf16 v[114:117], v[170:173], v[188:191], v[114:117]
	v_mfma_f32_16x16x32_bf16 v[102:105], v[162:165], v[196:199], v[102:105]
	v_mfma_f32_16x16x32_bf16 v[98:101], v[170:173], v[196:199], v[98:101]
	v_mfma_f32_16x16x32_bf16 v[86:89], v[162:165], v[204:207], v[86:89]
	v_mfma_f32_16x16x32_bf16 v[82:85], v[170:173], v[204:207], v[82:85]
	v_mfma_f32_16x16x32_bf16 v[70:73], v[162:165], v[222:225], v[70:73]
	v_mfma_f32_16x16x32_bf16 v[66:69], v[170:173], v[222:225], v[66:69]
	v_mfma_f32_16x16x32_bf16 v[118:121], v[166:169], v[192:195], v[118:121]
	v_mfma_f32_16x16x32_bf16 v[114:117], v[174:177], v[192:195], v[114:117]
	v_mfma_f32_16x16x32_bf16 v[102:105], v[166:169], v[200:203], v[102:105]
	v_mfma_f32_16x16x32_bf16 v[98:101], v[174:177], v[200:203], v[98:101]
	v_mfma_f32_16x16x32_bf16 v[86:89], v[166:169], v[218:221], v[86:89]
	v_mfma_f32_16x16x32_bf16 v[82:85], v[174:177], v[218:221], v[82:85]
	v_mfma_f32_16x16x32_bf16 v[70:73], v[166:169], v[226:229], v[70:73]
	v_mfma_f32_16x16x32_bf16 v[66:69], v[174:177], v[226:229], v[66:69]
	s_setprio 0
	s_barrier
	s_add_i32 s42, s42, s2
	v_lshl_add_u64 v[152:153], s[18:19], 0, v[0:1]
	s_mov_b32 m0, s42
	ds_read_b128 v[188:191], v157 offset:16384
	ds_read_b128 v[192:195], v157 offset:17408
	ds_read_b128 v[196:199], v157 offset:18432
	ds_read_b128 v[200:203], v157 offset:19456
	ds_read_b128 v[204:207], v157 offset:20480
	ds_read_b128 v[218:221], v157 offset:21504
	ds_read_b128 v[222:225], v157 offset:22528
	ds_read_b128 v[226:229], v157 offset:23552
	global_load_lds_dwordx4 v[152:153], off
	s_add_i32 m0, s42, 0x2000
	s_add_u32 s44, s18, 0x80000
	v_lshl_add_u64 v[178:179], s[18:19], 0, v[130:131]
	s_addc_u32 s45, s19, 0
	s_add_i32 s3, s3, s2
	global_load_lds_dwordx4 v[178:179], off
	v_lshl_add_u64 v[180:181], s[44:45], 0, v[0:1]
	s_mov_b32 m0, s3
	v_lshl_add_u64 v[182:183], s[20:21], 0, v[132:133]
	global_load_lds_dwordx4 v[180:181], off
	v_lshl_add_u64 v[180:181], s[44:45], 0, v[130:131]
	s_add_i32 m0, s3, 0x2000
	s_nop 0
	global_load_lds_dwordx4 v[180:181], off
	v_lshl_add_u64 v[180:181], s[20:21], 0, v[134:135]
	s_mov_b32 m0, s22
	s_nop 0
	global_load_lds_dwordx4 v[180:181], off
	s_mov_b32 m0, s23
	s_nop 0
	global_load_lds_dwordx4 v[182:183], off
	s_waitcnt vmcnt(8)
	s_waitcnt lgkmcnt(0)
	v_mfma_f32_16x16x32_bf16 v[62:65], v[140:143], v[188:191], v[62:65]
	v_mfma_f32_16x16x32_bf16 v[58:61], v[148:151], v[188:191], v[58:61]
	s_barrier
	s_setprio 1
	v_mfma_f32_16x16x32_bf16 v[46:49], v[140:143], v[196:199], v[46:49]
	v_mfma_f32_16x16x32_bf16 v[42:45], v[148:151], v[196:199], v[42:45]
	v_mfma_f32_16x16x32_bf16 v[30:33], v[140:143], v[204:207], v[30:33]
	v_mfma_f32_16x16x32_bf16 v[26:29], v[148:151], v[204:207], v[26:29]
	v_mfma_f32_16x16x32_bf16 v[14:17], v[140:143], v[222:225], v[14:17]
	v_mfma_f32_16x16x32_bf16 v[6:9], v[148:151], v[222:225], v[6:9]
	v_mfma_f32_16x16x32_bf16 v[62:65], v[144:147], v[192:195], v[62:65]
	v_mfma_f32_16x16x32_bf16 v[58:61], v[158:161], v[192:195], v[58:61]
	v_mfma_f32_16x16x32_bf16 v[46:49], v[144:147], v[200:203], v[46:49]
	v_mfma_f32_16x16x32_bf16 v[42:45], v[158:161], v[200:203], v[42:45]
	v_mfma_f32_16x16x32_bf16 v[30:33], v[144:147], v[218:221], v[30:33]
	v_mfma_f32_16x16x32_bf16 v[26:29], v[158:161], v[218:221], v[26:29]
	v_mfma_f32_16x16x32_bf16 v[14:17], v[144:147], v[226:229], v[14:17]
	v_mfma_f32_16x16x32_bf16 v[6:9], v[158:161], v[226:229], v[6:9]
	s_setprio 0
	s_setprio 1
	v_mfma_f32_16x16x32_bf16 v[54:57], v[162:165], v[188:191], v[54:57]
	v_mfma_f32_16x16x32_bf16 v[50:53], v[170:173], v[188:191], v[50:53]
	v_mfma_f32_16x16x32_bf16 v[38:41], v[162:165], v[196:199], v[38:41]
	v_mfma_f32_16x16x32_bf16 v[34:37], v[170:173], v[196:199], v[34:37]
	v_mfma_f32_16x16x32_bf16 v[22:25], v[162:165], v[204:207], v[22:25]
	v_mfma_f32_16x16x32_bf16 v[18:21], v[170:173], v[204:207], v[18:21]
	v_mfma_f32_16x16x32_bf16 v[10:13], v[162:165], v[222:225], v[10:13]
	v_mfma_f32_16x16x32_bf16 v[2:5], v[170:173], v[222:225], v[2:5]
	v_mfma_f32_16x16x32_bf16 v[54:57], v[166:169], v[192:195], v[54:57]
	v_mfma_f32_16x16x32_bf16 v[50:53], v[174:177], v[192:195], v[50:53]
	v_mfma_f32_16x16x32_bf16 v[38:41], v[166:169], v[200:203], v[38:41]
	v_mfma_f32_16x16x32_bf16 v[34:37], v[174:177], v[200:203], v[34:37]
	v_mfma_f32_16x16x32_bf16 v[22:25], v[166:169], v[218:221], v[22:25]
	v_mfma_f32_16x16x32_bf16 v[18:21], v[174:177], v[218:221], v[18:21]
	v_mfma_f32_16x16x32_bf16 v[10:13], v[166:169], v[226:229], v[10:13]
	v_mfma_f32_16x16x32_bf16 v[2:5], v[174:177], v[226:229], v[2:5]
	s_setprio 0
	s_barrier
	s_add_i32 s3, 0, 0x18000
	s_add_i32 s42, 0, 0x1c000
	v_add_u32_e32 v158, s3, v155
	v_add_u32_e32 v174, s42, v155
	ds_read_b128 v[140:143], v158
	ds_read_b128 v[144:147], v158 offset:1024
	ds_read_b128 v[148:151], v158 offset:2048
	ds_read_b128 v[158:161], v158 offset:3072
	ds_read_b128 v[162:165], v174
	ds_read_b128 v[166:169], v174 offset:1024
	ds_read_b128 v[170:173], v174 offset:2048
	ds_read_b128 v[174:177], v174 offset:3072
	s_add_u32 s20, s20, 0x80000
	s_addc_u32 s21, s21, 0
	s_mov_b32 m0, s24
	v_lshl_add_u64 v[184:185], s[20:21], 0, v[134:135]
	ds_read_b128 v[188:191], v157 offset:32768
	ds_read_b128 v[192:195], v157 offset:33792
	ds_read_b128 v[196:199], v157 offset:34816
	ds_read_b128 v[200:203], v157 offset:35840
	ds_read_b128 v[204:207], v157 offset:36864
	ds_read_b128 v[218:221], v157 offset:37888
	ds_read_b128 v[222:225], v157 offset:38912
	ds_read_b128 v[226:229], v157 offset:39936
	global_load_lds_dwordx4 v[184:185], off
	v_lshl_add_u64 v[184:185], s[20:21], 0, v[132:133]
	s_mov_b32 m0, s25
	s_nop 0
	global_load_lds_dwordx4 v[184:185], off
	s_waitcnt vmcnt(8)
	s_waitcnt lgkmcnt(0)
	v_mfma_f32_16x16x32_bf16 v[126:129], v[140:143], v[188:191], v[126:129]
	v_mfma_f32_16x16x32_bf16 v[122:125], v[148:151], v[188:191], v[122:125]
	s_barrier
	s_setprio 1
	v_mfma_f32_16x16x32_bf16 v[110:113], v[140:143], v[196:199], v[110:113]
	v_mfma_f32_16x16x32_bf16 v[106:109], v[148:151], v[196:199], v[106:109]
	v_mfma_f32_16x16x32_bf16 v[94:97], v[140:143], v[204:207], v[94:97]
	v_mfma_f32_16x16x32_bf16 v[90:93], v[148:151], v[204:207], v[90:93]
	v_mfma_f32_16x16x32_bf16 v[78:81], v[140:143], v[222:225], v[78:81]
	v_mfma_f32_16x16x32_bf16 v[74:77], v[148:151], v[222:225], v[74:77]
	v_mfma_f32_16x16x32_bf16 v[126:129], v[144:147], v[192:195], v[126:129]
	v_mfma_f32_16x16x32_bf16 v[122:125], v[158:161], v[192:195], v[122:125]
	v_mfma_f32_16x16x32_bf16 v[110:113], v[144:147], v[200:203], v[110:113]
	v_mfma_f32_16x16x32_bf16 v[106:109], v[158:161], v[200:203], v[106:109]
	v_mfma_f32_16x16x32_bf16 v[94:97], v[144:147], v[218:221], v[94:97]
	v_mfma_f32_16x16x32_bf16 v[90:93], v[158:161], v[218:221], v[90:93]
	v_mfma_f32_16x16x32_bf16 v[78:81], v[144:147], v[226:229], v[78:81]
	v_mfma_f32_16x16x32_bf16 v[74:77], v[158:161], v[226:229], v[74:77]
	s_setprio 0
	s_setprio 1
	v_mfma_f32_16x16x32_bf16 v[118:121], v[162:165], v[188:191], v[118:121]
	v_mfma_f32_16x16x32_bf16 v[114:117], v[170:173], v[188:191], v[114:117]
	v_mfma_f32_16x16x32_bf16 v[102:105], v[162:165], v[196:199], v[102:105]
	v_mfma_f32_16x16x32_bf16 v[98:101], v[170:173], v[196:199], v[98:101]
	v_mfma_f32_16x16x32_bf16 v[86:89], v[162:165], v[204:207], v[86:89]
	v_mfma_f32_16x16x32_bf16 v[82:85], v[170:173], v[204:207], v[82:85]
	v_mfma_f32_16x16x32_bf16 v[70:73], v[162:165], v[222:225], v[70:73]
	v_mfma_f32_16x16x32_bf16 v[66:69], v[170:173], v[222:225], v[66:69]
	v_mfma_f32_16x16x32_bf16 v[118:121], v[166:169], v[192:195], v[118:121]
	v_mfma_f32_16x16x32_bf16 v[114:117], v[174:177], v[192:195], v[114:117]
	v_mfma_f32_16x16x32_bf16 v[102:105], v[166:169], v[200:203], v[102:105]
	v_mfma_f32_16x16x32_bf16 v[98:101], v[174:177], v[200:203], v[98:101]
	v_mfma_f32_16x16x32_bf16 v[86:89], v[166:169], v[218:221], v[86:89]
	v_mfma_f32_16x16x32_bf16 v[82:85], v[174:177], v[218:221], v[82:85]
	v_mfma_f32_16x16x32_bf16 v[70:73], v[166:169], v[226:229], v[70:73]
	v_mfma_f32_16x16x32_bf16 v[66:69], v[174:177], v[226:229], v[66:69]
	s_setprio 0
	s_barrier
	s_add_i32 s3, s3, s2
	v_lshl_add_u64 v[152:153], v[152:153], 0, s[52:53]
	s_mov_b32 m0, s3
	ds_read_b128 v[188:191], v157 offset:49152
	ds_read_b128 v[192:195], v157 offset:50176
	ds_read_b128 v[196:199], v157 offset:51200
	ds_read_b128 v[200:203], v157 offset:52224
	ds_read_b128 v[204:207], v157 offset:53248
	ds_read_b128 v[218:221], v157 offset:54272
	ds_read_b128 v[222:225], v157 offset:55296
	ds_read_b128 v[226:229], v157 offset:56320
	global_load_lds_dwordx4 v[152:153], off
	s_add_i32 m0, s3, 0x2000
	s_add_u32 s18, s18, 0x80080
	v_lshl_add_u64 v[152:153], v[178:179], 0, s[52:53]
	s_addc_u32 s19, s19, 0
	s_add_i32 s3, s42, s2
	global_load_lds_dwordx4 v[152:153], off
	v_lshl_add_u64 v[152:153], s[18:19], 0, v[0:1]
	s_mov_b32 m0, s3
	s_nop 0
	global_load_lds_dwordx4 v[152:153], off
	v_lshl_add_u64 v[152:153], s[18:19], 0, v[130:131]
	s_add_i32 m0, s3, 0x2000
	s_nop 0
	global_load_lds_dwordx4 v[152:153], off
	v_lshl_add_u64 v[152:153], v[180:181], 0, s[52:53]
	s_mov_b32 m0, s26
	s_nop 0
	global_load_lds_dwordx4 v[152:153], off
	v_lshl_add_u64 v[152:153], v[182:183], 0, s[52:53]
	s_mov_b32 m0, s27
	s_nop 0
	global_load_lds_dwordx4 v[152:153], off
	s_waitcnt vmcnt(8)
	s_waitcnt lgkmcnt(0)
	v_mfma_f32_16x16x32_bf16 v[62:65], v[140:143], v[188:191], v[62:65]
	v_mfma_f32_16x16x32_bf16 v[58:61], v[148:151], v[188:191], v[58:61]
	s_barrier
	s_setprio 1
	v_mfma_f32_16x16x32_bf16 v[46:49], v[140:143], v[196:199], v[46:49]
	v_mfma_f32_16x16x32_bf16 v[42:45], v[148:151], v[196:199], v[42:45]
	v_mfma_f32_16x16x32_bf16 v[30:33], v[140:143], v[204:207], v[30:33]
	v_mfma_f32_16x16x32_bf16 v[26:29], v[148:151], v[204:207], v[26:29]
	v_mfma_f32_16x16x32_bf16 v[14:17], v[140:143], v[222:225], v[14:17]
	v_mfma_f32_16x16x32_bf16 v[6:9], v[148:151], v[222:225], v[6:9]
	v_mfma_f32_16x16x32_bf16 v[62:65], v[144:147], v[192:195], v[62:65]
	v_mfma_f32_16x16x32_bf16 v[58:61], v[158:161], v[192:195], v[58:61]
	v_mfma_f32_16x16x32_bf16 v[46:49], v[144:147], v[200:203], v[46:49]
	v_mfma_f32_16x16x32_bf16 v[42:45], v[158:161], v[200:203], v[42:45]
	v_mfma_f32_16x16x32_bf16 v[30:33], v[144:147], v[218:221], v[30:33]
	v_mfma_f32_16x16x32_bf16 v[26:29], v[158:161], v[218:221], v[26:29]
	v_mfma_f32_16x16x32_bf16 v[14:17], v[144:147], v[226:229], v[14:17]
	v_mfma_f32_16x16x32_bf16 v[6:9], v[158:161], v[226:229], v[6:9]
	s_setprio 0
	s_setprio 1
	v_mfma_f32_16x16x32_bf16 v[54:57], v[162:165], v[188:191], v[54:57]
	v_mfma_f32_16x16x32_bf16 v[50:53], v[170:173], v[188:191], v[50:53]
	v_mfma_f32_16x16x32_bf16 v[38:41], v[162:165], v[196:199], v[38:41]
	v_mfma_f32_16x16x32_bf16 v[34:37], v[170:173], v[196:199], v[34:37]
	v_mfma_f32_16x16x32_bf16 v[22:25], v[162:165], v[204:207], v[22:25]
	v_mfma_f32_16x16x32_bf16 v[18:21], v[170:173], v[204:207], v[18:21]
	v_mfma_f32_16x16x32_bf16 v[10:13], v[162:165], v[222:225], v[10:13]
	v_mfma_f32_16x16x32_bf16 v[2:5], v[170:173], v[222:225], v[2:5]
	v_mfma_f32_16x16x32_bf16 v[54:57], v[166:169], v[192:195], v[54:57]
	v_mfma_f32_16x16x32_bf16 v[50:53], v[174:177], v[192:195], v[50:53]
	v_mfma_f32_16x16x32_bf16 v[38:41], v[166:169], v[200:203], v[38:41]
	v_mfma_f32_16x16x32_bf16 v[34:37], v[174:177], v[200:203], v[34:37]
	v_mfma_f32_16x16x32_bf16 v[22:25], v[166:169], v[218:221], v[22:25]
	v_mfma_f32_16x16x32_bf16 v[18:21], v[174:177], v[218:221], v[18:21]
	v_mfma_f32_16x16x32_bf16 v[10:13], v[166:169], v[226:229], v[10:13]
	v_mfma_f32_16x16x32_bf16 v[2:5], v[174:177], v[226:229], v[2:5]
	s_setprio 0
	s_barrier
	s_add_i32 s41, s41, 2
	s_add_u32 s16, s16, 0x100
	s_addc_u32 s17, s17, 0
	s_add_u32 s35, s35, 0x100
	s_addc_u32 s40, s40, 0
	s_cmp_gt_u32 s41, 29
	s_cbranch_scc0 .LBB0_377
	s_and_b64 vcc, exec, s[6:7]
	s_movk_i32 s40, 0x4000
	s_movk_i32 s41, 0x6000
	s_cbranch_vccz .LBB0_380
	s_barrier

.LBB0_399:
	s_add_u32 s3, s0, 0xfff80080
	s_addc_u32 s4, s1, -1
	s_add_i32 s42, 0, 0x10000
	s_cmp_eq_u32 s46, 28
	s_cselect_b32 s7, s8, s4
	s_cselect_b32 s6, s9, s3
	v_add_u32_e32 v0, s42, v206
	s_cselect_b32 s5, s19, s27
	s_cselect_b32 s4, s21, s26
	s_add_i32 s3, 0, 0x14000
	ds_read_b128 v[130:133], v0
	ds_read_b128 v[134:137], v0 offset:1024
	ds_read_b128 v[138:141], v0 offset:2048
	ds_read_b128 v[142:145], v0 offset:3072
	v_add_u32_e32 v0, s3, v206
	ds_read_b128 v[146:149], v0
	ds_read_b128 v[150:153], v0 offset:1024
	s_waitcnt lgkmcnt(0)
	ds_read_b128 v[154:157], v0 offset:2048
	ds_read_b128 v[158:161], v0 offset:3072
	v_lshl_add_u64 v[176:177], s[0:1], 0, v[170:171]
	s_add_i32 m0, s28, 0xc000
	ds_read_b128 v[196:199], v218
	ds_read_b128 v[200:203], v218 offset:1024
	ds_read_b128 v[220:223], v218 offset:2048
	ds_read_b128 v[224:227], v218 offset:3072
	ds_read_b128 v[228:231], v218 offset:4096
	ds_read_b128 v[232:235], v218 offset:5120
	ds_read_b128 v[236:239], v218 offset:6144
	ds_read_b128 v[240:243], v218 offset:7168
	global_load_lds_dwordx4 v[176:177], off
	v_lshl_add_u64 v[176:177], s[0:1], 0, v[172:173]
	s_add_i32 m0, s28, 0xe000
	s_nop 0
	global_load_lds_dwordx4 v[176:177], off
	s_waitcnt vmcnt(8)
	s_waitcnt lgkmcnt(0)
	v_mfma_f32_16x16x32_bf16 v[126:129], v[130:133], v[196:199], v[126:129]
	v_mfma_f32_16x16x32_bf16 v[122:125], v[138:141], v[196:199], v[122:125]
	s_barrier
	s_setprio 1
	v_mfma_f32_16x16x32_bf16 v[118:121], v[130:133], v[220:223], v[118:121]
	v_mfma_f32_16x16x32_bf16 v[114:117], v[138:141], v[220:223], v[114:117]
	v_mfma_f32_16x16x32_bf16 v[110:113], v[130:133], v[228:231], v[110:113]
	v_mfma_f32_16x16x32_bf16 v[106:109], v[138:141], v[228:231], v[106:109]
	v_mfma_f32_16x16x32_bf16 v[102:105], v[130:133], v[236:239], v[102:105]
	v_mfma_f32_16x16x32_bf16 v[98:101], v[138:141], v[236:239], v[98:101]
	v_mfma_f32_16x16x32_bf16 v[126:129], v[134:137], v[200:203], v[126:129]
	v_mfma_f32_16x16x32_bf16 v[122:125], v[142:145], v[200:203], v[122:125]
	v_mfma_f32_16x16x32_bf16 v[118:121], v[134:137], v[224:227], v[118:121]
	v_mfma_f32_16x16x32_bf16 v[114:117], v[142:145], v[224:227], v[114:117]
	v_mfma_f32_16x16x32_bf16 v[110:113], v[134:137], v[232:235], v[110:113]
	v_mfma_f32_16x16x32_bf16 v[106:109], v[142:145], v[232:235], v[106:109]
	v_mfma_f32_16x16x32_bf16 v[102:105], v[134:137], v[240:243], v[102:105]
	v_mfma_f32_16x16x32_bf16 v[98:101], v[142:145], v[240:243], v[98:101]
	s_setprio 0
	s_setprio 1
	v_mfma_f32_16x16x32_bf16 v[94:97], v[146:149], v[196:199], v[94:97]
	v_mfma_f32_16x16x32_bf16 v[90:93], v[154:157], v[196:199], v[90:93]
	v_mfma_f32_16x16x32_bf16 v[86:89], v[146:149], v[220:223], v[86:89]
	v_mfma_f32_16x16x32_bf16 v[82:85], v[154:157], v[220:223], v[82:85]
	v_mfma_f32_16x16x32_bf16 v[78:81], v[146:149], v[228:231], v[78:81]
	v_mfma_f32_16x16x32_bf16 v[74:77], v[154:157], v[228:231], v[74:77]
	v_mfma_f32_16x16x32_bf16 v[70:73], v[146:149], v[236:239], v[70:73]
	v_mfma_f32_16x16x32_bf16 v[66:69], v[154:157], v[236:239], v[66:69]
	v_mfma_f32_16x16x32_bf16 v[94:97], v[150:153], v[200:203], v[94:97]
	v_mfma_f32_16x16x32_bf16 v[90:93], v[158:161], v[200:203], v[90:93]
	v_mfma_f32_16x16x32_bf16 v[86:89], v[150:153], v[224:227], v[86:89]
	v_mfma_f32_16x16x32_bf16 v[82:85], v[158:161], v[224:227], v[82:85]
	v_mfma_f32_16x16x32_bf16 v[78:81], v[150:153], v[232:235], v[78:81]
	v_mfma_f32_16x16x32_bf16 v[74:77], v[158:161], v[232:235], v[74:77]
	v_mfma_f32_16x16x32_bf16 v[70:73], v[150:153], v[240:243], v[70:73]
	v_mfma_f32_16x16x32_bf16 v[66:69], v[158:161], v[240:243], v[66:69]
	s_setprio 0
	s_barrier
	s_add_i32 s42, s42, s2
	v_lshl_add_u64 v[176:177], s[4:5], 0, v[166:167]
	s_mov_b32 m0, s42
	ds_read_b128 v[196:199], v218 offset:16384
	ds_read_b128 v[200:203], v218 offset:17408
	ds_read_b128 v[220:223], v218 offset:18432
	ds_read_b128 v[224:227], v218 offset:19456
	ds_read_b128 v[228:231], v218 offset:20480
	ds_read_b128 v[232:235], v218 offset:21504
	ds_read_b128 v[236:239], v218 offset:22528
	ds_read_b128 v[240:243], v218 offset:23552
	global_load_lds_dwordx4 v[176:177], off
	s_add_i32 m0, s42, 0x2000
	s_add_u32 s56, s4, 0x80000
	v_lshl_add_u64 v[178:179], s[4:5], 0, v[162:163]
	s_addc_u32 s57, s5, 0
	s_add_i32 s3, s3, s2
	global_load_lds_dwordx4 v[178:179], off
	v_lshl_add_u64 v[244:245], s[56:57], 0, v[166:167]
	s_mov_b32 m0, s3
	v_lshl_add_u64 v[246:247], s[6:7], 0, v[164:165]
	global_load_lds_dwordx4 v[244:245], off
	v_lshl_add_u64 v[244:245], s[56:57], 0, v[162:163]
	s_add_i32 m0, s3, 0x2000
	s_nop 0
	global_load_lds_dwordx4 v[244:245], off
	v_lshl_add_u64 v[244:245], s[6:7], 0, v[168:169]
	s_mov_b32 m0, s28
	s_nop 0
	global_load_lds_dwordx4 v[244:245], off
	s_mov_b32 m0, s29
	s_nop 0
	global_load_lds_dwordx4 v[246:247], off
	s_waitcnt vmcnt(8)
	s_waitcnt lgkmcnt(0)
	v_mfma_f32_16x16x32_bf16 v[62:65], v[130:133], v[196:199], v[62:65]
	v_mfma_f32_16x16x32_bf16 v[58:61], v[138:141], v[196:199], v[58:61]
	s_barrier
	s_setprio 1
	v_mfma_f32_16x16x32_bf16 v[54:57], v[130:133], v[220:223], v[54:57]
	v_mfma_f32_16x16x32_bf16 v[50:53], v[138:141], v[220:223], v[50:53]
	v_mfma_f32_16x16x32_bf16 v[46:49], v[130:133], v[228:231], v[46:49]
	v_mfma_f32_16x16x32_bf16 v[42:45], v[138:141], v[228:231], v[42:45]
	v_mfma_f32_16x16x32_bf16 v[38:41], v[130:133], v[236:239], v[38:41]
	v_mfma_f32_16x16x32_bf16 v[34:37], v[138:141], v[236:239], v[34:37]
	v_mfma_f32_16x16x32_bf16 v[62:65], v[134:137], v[200:203], v[62:65]
	v_mfma_f32_16x16x32_bf16 v[58:61], v[142:145], v[200:203], v[58:61]
	v_mfma_f32_16x16x32_bf16 v[54:57], v[134:137], v[224:227], v[54:57]
	v_mfma_f32_16x16x32_bf16 v[50:53], v[142:145], v[224:227], v[50:53]
	v_mfma_f32_16x16x32_bf16 v[46:49], v[134:137], v[232:235], v[46:49]
	v_mfma_f32_16x16x32_bf16 v[42:45], v[142:145], v[232:235], v[42:45]
	v_mfma_f32_16x16x32_bf16 v[38:41], v[134:137], v[240:243], v[38:41]
	v_mfma_f32_16x16x32_bf16 v[34:37], v[142:145], v[240:243], v[34:37]
	s_setprio 0
	s_setprio 1
	v_mfma_f32_16x16x32_bf16 v[30:33], v[146:149], v[196:199], v[30:33]
	v_mfma_f32_16x16x32_bf16 v[26:29], v[154:157], v[196:199], v[26:29]
	v_mfma_f32_16x16x32_bf16 v[22:25], v[146:149], v[220:223], v[22:25]
	v_mfma_f32_16x16x32_bf16 v[18:21], v[154:157], v[220:223], v[18:21]
	v_mfma_f32_16x16x32_bf16 v[14:17], v[146:149], v[228:231], v[14:17]
	v_mfma_f32_16x16x32_bf16 v[10:13], v[154:157], v[228:231], v[10:13]
	v_mfma_f32_16x16x32_bf16 v[6:9], v[146:149], v[236:239], v[6:9]
	v_mfma_f32_16x16x32_bf16 v[2:5], v[154:157], v[236:239], v[2:5]
	v_mfma_f32_16x16x32_bf16 v[30:33], v[150:153], v[200:203], v[30:33]
	v_mfma_f32_16x16x32_bf16 v[26:29], v[158:161], v[200:203], v[26:29]
	v_mfma_f32_16x16x32_bf16 v[22:25], v[150:153], v[224:227], v[22:25]
	v_mfma_f32_16x16x32_bf16 v[18:21], v[158:161], v[224:227], v[18:21]
	v_mfma_f32_16x16x32_bf16 v[14:17], v[150:153], v[232:235], v[14:17]
	v_mfma_f32_16x16x32_bf16 v[10:13], v[158:161], v[232:235], v[10:13]
	v_mfma_f32_16x16x32_bf16 v[6:9], v[150:153], v[240:243], v[6:9]
	v_mfma_f32_16x16x32_bf16 v[2:5], v[158:161], v[240:243], v[2:5]
	s_setprio 0
	s_barrier
	s_add_i32 s3, 0, 0x18000
	v_add_u32_e32 v0, s3, v206
	s_add_i32 s42, 0, 0x1c000
	ds_read_b128 v[130:133], v0
	ds_read_b128 v[134:137], v0 offset:1024
	ds_read_b128 v[138:141], v0 offset:2048
	ds_read_b128 v[142:145], v0 offset:3072
	v_add_u32_e32 v0, s42, v206
	ds_read_b128 v[146:149], v0
	ds_read_b128 v[150:153], v0 offset:1024
	ds_read_b128 v[154:157], v0 offset:2048
	ds_read_b128 v[158:161], v0 offset:3072
	s_add_u32 s6, s6, 0x80000
	s_addc_u32 s7, s7, 0
	s_mov_b32 m0, s30
	v_lshl_add_u64 v[248:249], s[6:7], 0, v[168:169]
	ds_read_b128 v[196:199], v218 offset:32768
	ds_read_b128 v[200:203], v218 offset:33792
	ds_read_b128 v[220:223], v218 offset:34816
	ds_read_b128 v[224:227], v218 offset:35840
	ds_read_b128 v[228:231], v218 offset:36864
	ds_read_b128 v[232:235], v218 offset:37888
	ds_read_b128 v[236:239], v218 offset:38912
	ds_read_b128 v[240:243], v218 offset:39936
	global_load_lds_dwordx4 v[248:249], off
	v_lshl_add_u64 v[248:249], s[6:7], 0, v[164:165]
	s_mov_b32 m0, s31
	s_nop 0
	global_load_lds_dwordx4 v[248:249], off
	s_waitcnt vmcnt(8)
	s_waitcnt lgkmcnt(0)
	v_mfma_f32_16x16x32_bf16 v[126:129], v[130:133], v[196:199], v[126:129]
	v_mfma_f32_16x16x32_bf16 v[122:125], v[138:141], v[196:199], v[122:125]
	s_barrier
	s_setprio 1
	v_mfma_f32_16x16x32_bf16 v[118:121], v[130:133], v[220:223], v[118:121]
	v_mfma_f32_16x16x32_bf16 v[114:117], v[138:141], v[220:223], v[114:117]
	v_mfma_f32_16x16x32_bf16 v[110:113], v[130:133], v[228:231], v[110:113]
	v_mfma_f32_16x16x32_bf16 v[106:109], v[138:141], v[228:231], v[106:109]
	v_mfma_f32_16x16x32_bf16 v[102:105], v[130:133], v[236:239], v[102:105]
	v_mfma_f32_16x16x32_bf16 v[98:101], v[138:141], v[236:239], v[98:101]
	v_mfma_f32_16x16x32_bf16 v[126:129], v[134:137], v[200:203], v[126:129]
	v_mfma_f32_16x16x32_bf16 v[122:125], v[142:145], v[200:203], v[122:125]
	v_mfma_f32_16x16x32_bf16 v[118:121], v[134:137], v[224:227], v[118:121]
	v_mfma_f32_16x16x32_bf16 v[114:117], v[142:145], v[224:227], v[114:117]
	v_mfma_f32_16x16x32_bf16 v[110:113], v[134:137], v[232:235], v[110:113]
	v_mfma_f32_16x16x32_bf16 v[106:109], v[142:145], v[232:235], v[106:109]
	v_mfma_f32_16x16x32_bf16 v[102:105], v[134:137], v[240:243], v[102:105]
	v_mfma_f32_16x16x32_bf16 v[98:101], v[142:145], v[240:243], v[98:101]
	s_setprio 0
	s_setprio 1
	v_mfma_f32_16x16x32_bf16 v[94:97], v[146:149], v[196:199], v[94:97]
	v_mfma_f32_16x16x32_bf16 v[90:93], v[154:157], v[196:199], v[90:93]
	v_mfma_f32_16x16x32_bf16 v[86:89], v[146:149], v[220:223], v[86:89]
	v_mfma_f32_16x16x32_bf16 v[82:85], v[154:157], v[220:223], v[82:85]
	v_mfma_f32_16x16x32_bf16 v[78:81], v[146:149], v[228:231], v[78:81]
	v_mfma_f32_16x16x32_bf16 v[74:77], v[154:157], v[228:231], v[74:77]
	v_mfma_f32_16x16x32_bf16 v[70:73], v[146:149], v[236:239], v[70:73]
	v_mfma_f32_16x16x32_bf16 v[66:69], v[154:157], v[236:239], v[66:69]
	v_mfma_f32_16x16x32_bf16 v[94:97], v[150:153], v[200:203], v[94:97]
	v_mfma_f32_16x16x32_bf16 v[90:93], v[158:161], v[200:203], v[90:93]
	v_mfma_f32_16x16x32_bf16 v[86:89], v[150:153], v[224:227], v[86:89]
	v_mfma_f32_16x16x32_bf16 v[82:85], v[158:161], v[224:227], v[82:85]
	v_mfma_f32_16x16x32_bf16 v[78:81], v[150:153], v[232:235], v[78:81]
	v_mfma_f32_16x16x32_bf16 v[74:77], v[158:161], v[232:235], v[74:77]
	v_mfma_f32_16x16x32_bf16 v[70:73], v[150:153], v[240:243], v[70:73]
	v_mfma_f32_16x16x32_bf16 v[66:69], v[158:161], v[240:243], v[66:69]
	s_setprio 0
	s_barrier
	s_add_i32 s3, s3, s2
	v_lshl_add_u64 v[176:177], v[176:177], 0, s[52:53]
	s_mov_b32 m0, s3
	ds_read_b128 v[196:199], v218 offset:49152
	ds_read_b128 v[200:203], v218 offset:50176
	ds_read_b128 v[220:223], v218 offset:51200
	ds_read_b128 v[224:227], v218 offset:52224
	ds_read_b128 v[228:231], v218 offset:53248
	ds_read_b128 v[232:235], v218 offset:54272
	ds_read_b128 v[236:239], v218 offset:55296
	ds_read_b128 v[240:243], v218 offset:56320
	global_load_lds_dwordx4 v[176:177], off
	s_add_i32 m0, s3, 0x2000
	s_add_u32 s4, s4, 0x80080
	v_lshl_add_u64 v[176:177], v[178:179], 0, s[52:53]
	s_addc_u32 s5, s5, 0
	s_add_i32 s3, s42, s2
	global_load_lds_dwordx4 v[176:177], off
	v_lshl_add_u64 v[176:177], s[4:5], 0, v[166:167]
	s_mov_b32 m0, s3
	s_nop 0
	global_load_lds_dwordx4 v[176:177], off
	v_lshl_add_u64 v[176:177], s[4:5], 0, v[162:163]
	s_add_i32 m0, s3, 0x2000
	s_nop 0
	global_load_lds_dwordx4 v[176:177], off
	v_lshl_add_u64 v[176:177], v[244:245], 0, s[52:53]
	s_mov_b32 m0, s35
	s_nop 0
	global_load_lds_dwordx4 v[176:177], off
	v_lshl_add_u64 v[176:177], v[246:247], 0, s[52:53]
	s_mov_b32 m0, s40
	s_nop 0
	global_load_lds_dwordx4 v[176:177], off
	s_waitcnt vmcnt(8)
	s_waitcnt lgkmcnt(0)
	v_mfma_f32_16x16x32_bf16 v[62:65], v[130:133], v[196:199], v[62:65]
	v_mfma_f32_16x16x32_bf16 v[58:61], v[138:141], v[196:199], v[58:61]
	s_barrier
	s_setprio 1
	v_mfma_f32_16x16x32_bf16 v[54:57], v[130:133], v[220:223], v[54:57]
	v_mfma_f32_16x16x32_bf16 v[50:53], v[138:141], v[220:223], v[50:53]
	v_mfma_f32_16x16x32_bf16 v[46:49], v[130:133], v[228:231], v[46:49]
	v_mfma_f32_16x16x32_bf16 v[42:45], v[138:141], v[228:231], v[42:45]
	v_mfma_f32_16x16x32_bf16 v[38:41], v[130:133], v[236:239], v[38:41]
	v_mfma_f32_16x16x32_bf16 v[34:37], v[138:141], v[236:239], v[34:37]
	v_mfma_f32_16x16x32_bf16 v[62:65], v[134:137], v[200:203], v[62:65]
	v_mfma_f32_16x16x32_bf16 v[58:61], v[142:145], v[200:203], v[58:61]
	v_mfma_f32_16x16x32_bf16 v[54:57], v[134:137], v[224:227], v[54:57]
	v_mfma_f32_16x16x32_bf16 v[50:53], v[142:145], v[224:227], v[50:53]
	v_mfma_f32_16x16x32_bf16 v[46:49], v[134:137], v[232:235], v[46:49]
	v_mfma_f32_16x16x32_bf16 v[42:45], v[142:145], v[232:235], v[42:45]
	v_mfma_f32_16x16x32_bf16 v[38:41], v[134:137], v[240:243], v[38:41]
	v_mfma_f32_16x16x32_bf16 v[34:37], v[142:145], v[240:243], v[34:37]
	s_setprio 0
	s_setprio 1
	v_mfma_f32_16x16x32_bf16 v[30:33], v[146:149], v[196:199], v[30:33]
	v_mfma_f32_16x16x32_bf16 v[26:29], v[154:157], v[196:199], v[26:29]
	v_mfma_f32_16x16x32_bf16 v[22:25], v[146:149], v[220:223], v[22:25]
	v_mfma_f32_16x16x32_bf16 v[18:21], v[154:157], v[220:223], v[18:21]
	v_mfma_f32_16x16x32_bf16 v[14:17], v[146:149], v[228:231], v[14:17]
	v_mfma_f32_16x16x32_bf16 v[10:13], v[154:157], v[228:231], v[10:13]
	v_mfma_f32_16x16x32_bf16 v[6:9], v[146:149], v[236:239], v[6:9]
	v_mfma_f32_16x16x32_bf16 v[2:5], v[154:157], v[236:239], v[2:5]
	v_mfma_f32_16x16x32_bf16 v[30:33], v[150:153], v[200:203], v[30:33]
	v_mfma_f32_16x16x32_bf16 v[26:29], v[158:161], v[200:203], v[26:29]
	v_mfma_f32_16x16x32_bf16 v[22:25], v[150:153], v[224:227], v[22:25]
	v_mfma_f32_16x16x32_bf16 v[18:21], v[158:161], v[224:227], v[18:21]
	v_mfma_f32_16x16x32_bf16 v[14:17], v[150:153], v[232:235], v[14:17]
	v_mfma_f32_16x16x32_bf16 v[10:13], v[158:161], v[232:235], v[10:13]
	v_mfma_f32_16x16x32_bf16 v[6:9], v[150:153], v[240:243], v[6:9]
	v_mfma_f32_16x16x32_bf16 v[2:5], v[158:161], v[240:243], v[2:5]
	s_setprio 0
	s_barrier
	s_add_i32 s46, s46, 2
	s_add_u32 s0, s0, 0x100
	s_addc_u32 s1, s1, 0
	s_add_u32 s26, s26, 0x100
	s_addc_u32 s27, s27, 0
	s_cmp_gt_u32 s46, 29
	s_cbranch_scc0 .LBB0_399
	s_and_b64 vcc, exec, s[14:15]
	s_cbranch_vccz .LBB0_402
	s_barrier

.LBB0_846:
	s_add_u32 s3, s0, 0xfff80080
	s_addc_u32 s18, s1, -1
	s_add_i32 s42, 0, 0x10000
	s_cmp_eq_u32 s41, 28
	s_cselect_b32 s21, s13, s18
	s_cselect_b32 s20, s31, s3
	s_cselect_b32 s19, s11, s40
	s_cselect_b32 s18, s34, s35
	s_add_i32 s3, 0, 0x14000
	v_add_u32_e32 v152, s42, v163
	v_add_u32_e32 v160, s3, v163
	ds_read_b128 v[140:143], v152
	ds_read_b128 v[144:147], v152 offset:1024
	ds_read_b128 v[148:151], v152 offset:2048
	ds_read_b128 v[152:155], v152 offset:3072
	ds_read_b128 v[156:159], v160
	ds_read_b128 v[166:169], v160 offset:1024
	ds_read_b128 v[170:173], v160 offset:2048
	ds_read_b128 v[174:177], v160 offset:3072
	v_lshl_add_u64 v[160:161], s[0:1], 0, v[136:137]
	s_add_i32 m0, s22, 0xc000
	ds_read_b128 v[188:191], v165
	ds_read_b128 v[192:195], v165 offset:1024
	ds_read_b128 v[196:199], v165 offset:2048
	ds_read_b128 v[200:203], v165 offset:3072
	ds_read_b128 v[204:207], v165 offset:4096
	ds_read_b128 v[218:221], v165 offset:5120
	ds_read_b128 v[222:225], v165 offset:6144
	ds_read_b128 v[226:229], v165 offset:7168
	global_load_lds_dwordx4 v[160:161], off
	v_lshl_add_u64 v[160:161], s[0:1], 0, v[138:139]
	s_add_i32 m0, s22, 0xe000
	s_nop 0
	global_load_lds_dwordx4 v[160:161], off
	s_waitcnt vmcnt(8)
	s_waitcnt lgkmcnt(0)
	v_mfma_f32_16x16x32_bf16 v[126:129], v[140:143], v[188:191], v[126:129]
	v_mfma_f32_16x16x32_bf16 v[122:125], v[148:151], v[188:191], v[122:125]
	s_barrier
	s_setprio 1
	v_mfma_f32_16x16x32_bf16 v[110:113], v[140:143], v[196:199], v[110:113]
	v_mfma_f32_16x16x32_bf16 v[106:109], v[148:151], v[196:199], v[106:109]
	v_mfma_f32_16x16x32_bf16 v[94:97], v[140:143], v[204:207], v[94:97]
	v_mfma_f32_16x16x32_bf16 v[90:93], v[148:151], v[204:207], v[90:93]
	v_mfma_f32_16x16x32_bf16 v[78:81], v[140:143], v[222:225], v[78:81]
	v_mfma_f32_16x16x32_bf16 v[74:77], v[148:151], v[222:225], v[74:77]
	v_mfma_f32_16x16x32_bf16 v[126:129], v[144:147], v[192:195], v[126:129]
	v_mfma_f32_16x16x32_bf16 v[122:125], v[152:155], v[192:195], v[122:125]
	v_mfma_f32_16x16x32_bf16 v[110:113], v[144:147], v[200:203], v[110:113]
	v_mfma_f32_16x16x32_bf16 v[106:109], v[152:155], v[200:203], v[106:109]
	v_mfma_f32_16x16x32_bf16 v[94:97], v[144:147], v[218:221], v[94:97]
	v_mfma_f32_16x16x32_bf16 v[90:93], v[152:155], v[218:221], v[90:93]
	v_mfma_f32_16x16x32_bf16 v[78:81], v[144:147], v[226:229], v[78:81]
	v_mfma_f32_16x16x32_bf16 v[74:77], v[152:155], v[226:229], v[74:77]
	s_setprio 0
	s_setprio 1
	v_mfma_f32_16x16x32_bf16 v[118:121], v[156:159], v[188:191], v[118:121]
	v_mfma_f32_16x16x32_bf16 v[114:117], v[170:173], v[188:191], v[114:117]
	v_mfma_f32_16x16x32_bf16 v[102:105], v[156:159], v[196:199], v[102:105]
	v_mfma_f32_16x16x32_bf16 v[98:101], v[170:173], v[196:199], v[98:101]
	v_mfma_f32_16x16x32_bf16 v[86:89], v[156:159], v[204:207], v[86:89]
	v_mfma_f32_16x16x32_bf16 v[82:85], v[170:173], v[204:207], v[82:85]
	v_mfma_f32_16x16x32_bf16 v[70:73], v[156:159], v[222:225], v[70:73]
	v_mfma_f32_16x16x32_bf16 v[66:69], v[170:173], v[222:225], v[66:69]
	v_mfma_f32_16x16x32_bf16 v[118:121], v[166:169], v[192:195], v[118:121]
	v_mfma_f32_16x16x32_bf16 v[114:117], v[174:177], v[192:195], v[114:117]
	v_mfma_f32_16x16x32_bf16 v[102:105], v[166:169], v[200:203], v[102:105]
	v_mfma_f32_16x16x32_bf16 v[98:101], v[174:177], v[200:203], v[98:101]
	v_mfma_f32_16x16x32_bf16 v[86:89], v[166:169], v[218:221], v[86:89]
	v_mfma_f32_16x16x32_bf16 v[82:85], v[174:177], v[218:221], v[82:85]
	v_mfma_f32_16x16x32_bf16 v[70:73], v[166:169], v[226:229], v[70:73]
	v_mfma_f32_16x16x32_bf16 v[66:69], v[174:177], v[226:229], v[66:69]
	s_setprio 0
	s_barrier
	s_add_i32 s42, s42, s2
	v_lshl_add_u64 v[160:161], s[18:19], 0, v[0:1]
	s_mov_b32 m0, s42
	ds_read_b128 v[188:191], v165 offset:16384
	ds_read_b128 v[192:195], v165 offset:17408
	ds_read_b128 v[196:199], v165 offset:18432
	ds_read_b128 v[200:203], v165 offset:19456
	ds_read_b128 v[204:207], v165 offset:20480
	ds_read_b128 v[218:221], v165 offset:21504
	ds_read_b128 v[222:225], v165 offset:22528
	ds_read_b128 v[226:229], v165 offset:23552
	global_load_lds_dwordx4 v[160:161], off
	s_add_i32 m0, s42, 0x2000
	s_add_u32 s44, s18, 0x80000
	v_lshl_add_u64 v[178:179], s[18:19], 0, v[130:131]
	s_addc_u32 s45, s19, 0
	s_add_i32 s3, s3, s2
	global_load_lds_dwordx4 v[178:179], off
	v_lshl_add_u64 v[180:181], s[44:45], 0, v[0:1]
	s_mov_b32 m0, s3
	v_lshl_add_u64 v[182:183], s[20:21], 0, v[132:133]
	global_load_lds_dwordx4 v[180:181], off
	v_lshl_add_u64 v[180:181], s[44:45], 0, v[130:131]
	s_add_i32 m0, s3, 0x2000
	s_nop 0
	global_load_lds_dwordx4 v[180:181], off
	v_lshl_add_u64 v[180:181], s[20:21], 0, v[134:135]
	s_mov_b32 m0, s22
	s_nop 0
	global_load_lds_dwordx4 v[180:181], off
	s_mov_b32 m0, s23
	s_nop 0
	global_load_lds_dwordx4 v[182:183], off
	s_waitcnt vmcnt(8)
	s_waitcnt lgkmcnt(0)
	v_mfma_f32_16x16x32_bf16 v[62:65], v[140:143], v[188:191], v[62:65]
	v_mfma_f32_16x16x32_bf16 v[58:61], v[148:151], v[188:191], v[58:61]
	s_barrier
	s_setprio 1
	v_mfma_f32_16x16x32_bf16 v[46:49], v[140:143], v[196:199], v[46:49]
	v_mfma_f32_16x16x32_bf16 v[42:45], v[148:151], v[196:199], v[42:45]
	v_mfma_f32_16x16x32_bf16 v[30:33], v[140:143], v[204:207], v[30:33]
	v_mfma_f32_16x16x32_bf16 v[26:29], v[148:151], v[204:207], v[26:29]
	v_mfma_f32_16x16x32_bf16 v[14:17], v[140:143], v[222:225], v[14:17]
	v_mfma_f32_16x16x32_bf16 v[10:13], v[148:151], v[222:225], v[10:13]
	v_mfma_f32_16x16x32_bf16 v[62:65], v[144:147], v[192:195], v[62:65]
	v_mfma_f32_16x16x32_bf16 v[58:61], v[152:155], v[192:195], v[58:61]
	v_mfma_f32_16x16x32_bf16 v[46:49], v[144:147], v[200:203], v[46:49]
	v_mfma_f32_16x16x32_bf16 v[42:45], v[152:155], v[200:203], v[42:45]
	v_mfma_f32_16x16x32_bf16 v[30:33], v[144:147], v[218:221], v[30:33]
	v_mfma_f32_16x16x32_bf16 v[26:29], v[152:155], v[218:221], v[26:29]
	v_mfma_f32_16x16x32_bf16 v[14:17], v[144:147], v[226:229], v[14:17]
	v_mfma_f32_16x16x32_bf16 v[10:13], v[152:155], v[226:229], v[10:13]
	s_setprio 0
	s_setprio 1
	v_mfma_f32_16x16x32_bf16 v[54:57], v[156:159], v[188:191], v[54:57]
	v_mfma_f32_16x16x32_bf16 v[50:53], v[170:173], v[188:191], v[50:53]
	v_mfma_f32_16x16x32_bf16 v[38:41], v[156:159], v[196:199], v[38:41]
	v_mfma_f32_16x16x32_bf16 v[34:37], v[170:173], v[196:199], v[34:37]
	v_mfma_f32_16x16x32_bf16 v[22:25], v[156:159], v[204:207], v[22:25]
	v_mfma_f32_16x16x32_bf16 v[18:21], v[170:173], v[204:207], v[18:21]
	v_mfma_f32_16x16x32_bf16 v[6:9], v[156:159], v[222:225], v[6:9]
	v_mfma_f32_16x16x32_bf16 v[2:5], v[170:173], v[222:225], v[2:5]
	v_mfma_f32_16x16x32_bf16 v[54:57], v[166:169], v[192:195], v[54:57]
	v_mfma_f32_16x16x32_bf16 v[50:53], v[174:177], v[192:195], v[50:53]
	v_mfma_f32_16x16x32_bf16 v[38:41], v[166:169], v[200:203], v[38:41]
	v_mfma_f32_16x16x32_bf16 v[34:37], v[174:177], v[200:203], v[34:37]
	v_mfma_f32_16x16x32_bf16 v[22:25], v[166:169], v[218:221], v[22:25]
	v_mfma_f32_16x16x32_bf16 v[18:21], v[174:177], v[218:221], v[18:21]
	v_mfma_f32_16x16x32_bf16 v[6:9], v[166:169], v[226:229], v[6:9]
	v_mfma_f32_16x16x32_bf16 v[2:5], v[174:177], v[226:229], v[2:5]
	s_setprio 0
	s_barrier
	s_add_i32 s3, 0, 0x18000
	s_add_i32 s42, 0, 0x1c000
	v_add_u32_e32 v152, s3, v163
	v_add_u32_e32 v174, s42, v163
	ds_read_b128 v[140:143], v152
	ds_read_b128 v[144:147], v152 offset:1024
	ds_read_b128 v[148:151], v152 offset:2048
	ds_read_b128 v[152:155], v152 offset:3072
	ds_read_b128 v[156:159], v174
	ds_read_b128 v[166:169], v174 offset:1024
	ds_read_b128 v[170:173], v174 offset:2048
	ds_read_b128 v[174:177], v174 offset:3072
	s_add_u32 s20, s20, 0x80000
	s_addc_u32 s21, s21, 0
	s_mov_b32 m0, s24
	v_lshl_add_u64 v[184:185], s[20:21], 0, v[134:135]
	ds_read_b128 v[188:191], v165 offset:32768
	ds_read_b128 v[192:195], v165 offset:33792
	ds_read_b128 v[196:199], v165 offset:34816
	ds_read_b128 v[200:203], v165 offset:35840
	ds_read_b128 v[204:207], v165 offset:36864
	ds_read_b128 v[218:221], v165 offset:37888
	ds_read_b128 v[222:225], v165 offset:38912
	ds_read_b128 v[226:229], v165 offset:39936
	global_load_lds_dwordx4 v[184:185], off
	v_lshl_add_u64 v[184:185], s[20:21], 0, v[132:133]
	s_mov_b32 m0, s25
	s_nop 0
	global_load_lds_dwordx4 v[184:185], off
	s_waitcnt vmcnt(8)
	s_waitcnt lgkmcnt(0)
	v_mfma_f32_16x16x32_bf16 v[126:129], v[140:143], v[188:191], v[126:129]
	v_mfma_f32_16x16x32_bf16 v[122:125], v[148:151], v[188:191], v[122:125]
	s_barrier
	s_setprio 1
	v_mfma_f32_16x16x32_bf16 v[110:113], v[140:143], v[196:199], v[110:113]
	v_mfma_f32_16x16x32_bf16 v[106:109], v[148:151], v[196:199], v[106:109]
	v_mfma_f32_16x16x32_bf16 v[94:97], v[140:143], v[204:207], v[94:97]
	v_mfma_f32_16x16x32_bf16 v[90:93], v[148:151], v[204:207], v[90:93]
	v_mfma_f32_16x16x32_bf16 v[78:81], v[140:143], v[222:225], v[78:81]
	v_mfma_f32_16x16x32_bf16 v[74:77], v[148:151], v[222:225], v[74:77]
	v_mfma_f32_16x16x32_bf16 v[126:129], v[144:147], v[192:195], v[126:129]
	v_mfma_f32_16x16x32_bf16 v[122:125], v[152:155], v[192:195], v[122:125]
	v_mfma_f32_16x16x32_bf16 v[110:113], v[144:147], v[200:203], v[110:113]
	v_mfma_f32_16x16x32_bf16 v[106:109], v[152:155], v[200:203], v[106:109]
	v_mfma_f32_16x16x32_bf16 v[94:97], v[144:147], v[218:221], v[94:97]
	v_mfma_f32_16x16x32_bf16 v[90:93], v[152:155], v[218:221], v[90:93]
	v_mfma_f32_16x16x32_bf16 v[78:81], v[144:147], v[226:229], v[78:81]
	v_mfma_f32_16x16x32_bf16 v[74:77], v[152:155], v[226:229], v[74:77]
	s_setprio 0
	s_setprio 1
	v_mfma_f32_16x16x32_bf16 v[118:121], v[156:159], v[188:191], v[118:121]
	v_mfma_f32_16x16x32_bf16 v[114:117], v[170:173], v[188:191], v[114:117]
	v_mfma_f32_16x16x32_bf16 v[102:105], v[156:159], v[196:199], v[102:105]
	v_mfma_f32_16x16x32_bf16 v[98:101], v[170:173], v[196:199], v[98:101]
	v_mfma_f32_16x16x32_bf16 v[86:89], v[156:159], v[204:207], v[86:89]
	v_mfma_f32_16x16x32_bf16 v[82:85], v[170:173], v[204:207], v[82:85]
	v_mfma_f32_16x16x32_bf16 v[70:73], v[156:159], v[222:225], v[70:73]
	v_mfma_f32_16x16x32_bf16 v[66:69], v[170:173], v[222:225], v[66:69]
	v_mfma_f32_16x16x32_bf16 v[118:121], v[166:169], v[192:195], v[118:121]
	v_mfma_f32_16x16x32_bf16 v[114:117], v[174:177], v[192:195], v[114:117]
	v_mfma_f32_16x16x32_bf16 v[102:105], v[166:169], v[200:203], v[102:105]
	v_mfma_f32_16x16x32_bf16 v[98:101], v[174:177], v[200:203], v[98:101]
	v_mfma_f32_16x16x32_bf16 v[86:89], v[166:169], v[218:221], v[86:89]
	v_mfma_f32_16x16x32_bf16 v[82:85], v[174:177], v[218:221], v[82:85]
	v_mfma_f32_16x16x32_bf16 v[70:73], v[166:169], v[226:229], v[70:73]
	v_mfma_f32_16x16x32_bf16 v[66:69], v[174:177], v[226:229], v[66:69]
	s_setprio 0
	s_barrier
	s_add_i32 s3, s3, s2
	v_lshl_add_u64 v[160:161], v[160:161], 0, s[52:53]
	s_mov_b32 m0, s3
	ds_read_b128 v[188:191], v165 offset:49152
	ds_read_b128 v[192:195], v165 offset:50176
	ds_read_b128 v[196:199], v165 offset:51200
	ds_read_b128 v[200:203], v165 offset:52224
	ds_read_b128 v[204:207], v165 offset:53248
	ds_read_b128 v[218:221], v165 offset:54272
	ds_read_b128 v[222:225], v165 offset:55296
	ds_read_b128 v[226:229], v165 offset:56320
	global_load_lds_dwordx4 v[160:161], off
	s_add_i32 m0, s3, 0x2000
	s_add_u32 s18, s18, 0x80080
	v_lshl_add_u64 v[160:161], v[178:179], 0, s[52:53]
	s_addc_u32 s19, s19, 0
	s_add_i32 s3, s42, s2
	global_load_lds_dwordx4 v[160:161], off
	v_lshl_add_u64 v[160:161], s[18:19], 0, v[0:1]
	s_mov_b32 m0, s3
	s_nop 0
	global_load_lds_dwordx4 v[160:161], off
	v_lshl_add_u64 v[160:161], s[18:19], 0, v[130:131]
	s_add_i32 m0, s3, 0x2000
	s_nop 0
	global_load_lds_dwordx4 v[160:161], off
	v_lshl_add_u64 v[160:161], v[180:181], 0, s[52:53]
	s_mov_b32 m0, s26
	s_nop 0
	global_load_lds_dwordx4 v[160:161], off
	v_lshl_add_u64 v[160:161], v[182:183], 0, s[52:53]
	s_mov_b32 m0, s27
	s_nop 0
	global_load_lds_dwordx4 v[160:161], off
	s_waitcnt vmcnt(8)
	s_waitcnt lgkmcnt(0)
	v_mfma_f32_16x16x32_bf16 v[62:65], v[140:143], v[188:191], v[62:65]
	v_mfma_f32_16x16x32_bf16 v[58:61], v[148:151], v[188:191], v[58:61]
	s_barrier
	s_setprio 1
	v_mfma_f32_16x16x32_bf16 v[46:49], v[140:143], v[196:199], v[46:49]
	v_mfma_f32_16x16x32_bf16 v[42:45], v[148:151], v[196:199], v[42:45]
	v_mfma_f32_16x16x32_bf16 v[30:33], v[140:143], v[204:207], v[30:33]
	v_mfma_f32_16x16x32_bf16 v[26:29], v[148:151], v[204:207], v[26:29]
	v_mfma_f32_16x16x32_bf16 v[14:17], v[140:143], v[222:225], v[14:17]
	v_mfma_f32_16x16x32_bf16 v[10:13], v[148:151], v[222:225], v[10:13]
	v_mfma_f32_16x16x32_bf16 v[62:65], v[144:147], v[192:195], v[62:65]
	v_mfma_f32_16x16x32_bf16 v[58:61], v[152:155], v[192:195], v[58:61]
	v_mfma_f32_16x16x32_bf16 v[46:49], v[144:147], v[200:203], v[46:49]
	v_mfma_f32_16x16x32_bf16 v[42:45], v[152:155], v[200:203], v[42:45]
	v_mfma_f32_16x16x32_bf16 v[30:33], v[144:147], v[218:221], v[30:33]
	v_mfma_f32_16x16x32_bf16 v[26:29], v[152:155], v[218:221], v[26:29]
	v_mfma_f32_16x16x32_bf16 v[14:17], v[144:147], v[226:229], v[14:17]
	v_mfma_f32_16x16x32_bf16 v[10:13], v[152:155], v[226:229], v[10:13]
	s_setprio 0
	s_setprio 1
	v_mfma_f32_16x16x32_bf16 v[54:57], v[156:159], v[188:191], v[54:57]
	v_mfma_f32_16x16x32_bf16 v[50:53], v[170:173], v[188:191], v[50:53]
	v_mfma_f32_16x16x32_bf16 v[38:41], v[156:159], v[196:199], v[38:41]
	v_mfma_f32_16x16x32_bf16 v[34:37], v[170:173], v[196:199], v[34:37]
	v_mfma_f32_16x16x32_bf16 v[22:25], v[156:159], v[204:207], v[22:25]
	v_mfma_f32_16x16x32_bf16 v[18:21], v[170:173], v[204:207], v[18:21]
	v_mfma_f32_16x16x32_bf16 v[6:9], v[156:159], v[222:225], v[6:9]
	v_mfma_f32_16x16x32_bf16 v[2:5], v[170:173], v[222:225], v[2:5]
	v_mfma_f32_16x16x32_bf16 v[54:57], v[166:169], v[192:195], v[54:57]
	v_mfma_f32_16x16x32_bf16 v[50:53], v[174:177], v[192:195], v[50:53]
	v_mfma_f32_16x16x32_bf16 v[38:41], v[166:169], v[200:203], v[38:41]
	v_mfma_f32_16x16x32_bf16 v[34:37], v[174:177], v[200:203], v[34:37]
	v_mfma_f32_16x16x32_bf16 v[22:25], v[166:169], v[218:221], v[22:25]
	v_mfma_f32_16x16x32_bf16 v[18:21], v[174:177], v[218:221], v[18:21]
	v_mfma_f32_16x16x32_bf16 v[6:9], v[166:169], v[226:229], v[6:9]
	v_mfma_f32_16x16x32_bf16 v[2:5], v[174:177], v[226:229], v[2:5]
	s_setprio 0
	s_barrier
	s_add_i32 s41, s41, 2
	s_add_u32 s0, s0, 0x100
	s_addc_u32 s1, s1, 0
	s_add_u32 s35, s35, 0x100
	s_addc_u32 s40, s40, 0
	s_cmp_gt_u32 s41, 29
	s_cbranch_scc0 .LBB0_846
	s_and_b64 vcc, exec, s[8:9]
	s_movk_i32 s40, 0x4000
	s_movk_i32 s41, 0x6000
	s_cbranch_vccz .LBB0_849
	s_barrier

.LBB0_959:
	s_add_u32 s3, s16, 0xfff80080
	s_addc_u32 s18, s17, -1
	s_add_i32 s42, 0, 0x10000
	s_cmp_eq_u32 s46, 28
	s_cselect_b32 s21, s11, s18
	s_cselect_b32 s20, s40, s3
	v_add_u32_e32 v140, s42, v143
	s_cselect_b32 s19, s9, s45
	s_cselect_b32 s18, s41, s44
	s_add_i32 s3, 0, 0x14000
	ds_read_b128 v[146:149], v140
	ds_read_b128 v[150:153], v140 offset:1024
	ds_read_b128 v[154:157], v140 offset:2048
	ds_read_b128 v[158:161], v140 offset:3072
	v_add_u32_e32 v140, s3, v143
	ds_read_b128 v[162:165], v140
	ds_read_b128 v[166:169], v140 offset:1024
	ds_read_b128 v[170:173], v140 offset:2048
	ds_read_b128 v[174:177], v140 offset:3072
	v_lshl_add_u64 v[140:141], s[16:17], 0, v[136:137]
	s_add_i32 m0, s25, 0xc000
	ds_read_b128 v[188:191], v145
	ds_read_b128 v[192:195], v145 offset:1024
	ds_read_b128 v[196:199], v145 offset:2048
	ds_read_b128 v[200:203], v145 offset:3072
	ds_read_b128 v[204:207], v145 offset:4096
	ds_read_b128 v[218:221], v145 offset:5120
	ds_read_b128 v[222:225], v145 offset:6144
	ds_read_b128 v[226:229], v145 offset:7168
	global_load_lds_dwordx4 v[140:141], off
	v_lshl_add_u64 v[140:141], s[16:17], 0, v[138:139]
	s_add_i32 m0, s25, 0xe000
	s_nop 0
	global_load_lds_dwordx4 v[140:141], off
	s_waitcnt vmcnt(8)
	s_waitcnt lgkmcnt(0)
	v_mfma_f32_16x16x32_bf16 v[126:129], v[146:149], v[188:191], v[126:129]
	v_mfma_f32_16x16x32_bf16 v[122:125], v[154:157], v[188:191], v[122:125]
	s_barrier
	s_setprio 1
	v_mfma_f32_16x16x32_bf16 v[110:113], v[146:149], v[196:199], v[110:113]
	v_mfma_f32_16x16x32_bf16 v[106:109], v[154:157], v[196:199], v[106:109]
	v_mfma_f32_16x16x32_bf16 v[94:97], v[146:149], v[204:207], v[94:97]
	v_mfma_f32_16x16x32_bf16 v[90:93], v[154:157], v[204:207], v[90:93]
	v_mfma_f32_16x16x32_bf16 v[78:81], v[146:149], v[222:225], v[78:81]
	v_mfma_f32_16x16x32_bf16 v[74:77], v[154:157], v[222:225], v[74:77]
	v_mfma_f32_16x16x32_bf16 v[126:129], v[150:153], v[192:195], v[126:129]
	v_mfma_f32_16x16x32_bf16 v[122:125], v[158:161], v[192:195], v[122:125]
	v_mfma_f32_16x16x32_bf16 v[110:113], v[150:153], v[200:203], v[110:113]
	v_mfma_f32_16x16x32_bf16 v[106:109], v[158:161], v[200:203], v[106:109]
	v_mfma_f32_16x16x32_bf16 v[94:97], v[150:153], v[218:221], v[94:97]
	v_mfma_f32_16x16x32_bf16 v[90:93], v[158:161], v[218:221], v[90:93]
	v_mfma_f32_16x16x32_bf16 v[78:81], v[150:153], v[226:229], v[78:81]
	v_mfma_f32_16x16x32_bf16 v[74:77], v[158:161], v[226:229], v[74:77]
	s_setprio 0
	s_setprio 1
	v_mfma_f32_16x16x32_bf16 v[118:121], v[162:165], v[188:191], v[118:121]
	v_mfma_f32_16x16x32_bf16 v[114:117], v[170:173], v[188:191], v[114:117]
	v_mfma_f32_16x16x32_bf16 v[102:105], v[162:165], v[196:199], v[102:105]
	v_mfma_f32_16x16x32_bf16 v[98:101], v[170:173], v[196:199], v[98:101]
	v_mfma_f32_16x16x32_bf16 v[86:89], v[162:165], v[204:207], v[86:89]
	v_mfma_f32_16x16x32_bf16 v[82:85], v[170:173], v[204:207], v[82:85]
	v_mfma_f32_16x16x32_bf16 v[70:73], v[162:165], v[222:225], v[70:73]
	v_mfma_f32_16x16x32_bf16 v[66:69], v[170:173], v[222:225], v[66:69]
	v_mfma_f32_16x16x32_bf16 v[118:121], v[166:169], v[192:195], v[118:121]
	v_mfma_f32_16x16x32_bf16 v[114:117], v[174:177], v[192:195], v[114:117]
	v_mfma_f32_16x16x32_bf16 v[102:105], v[166:169], v[200:203], v[102:105]
	v_mfma_f32_16x16x32_bf16 v[98:101], v[174:177], v[200:203], v[98:101]
	v_mfma_f32_16x16x32_bf16 v[86:89], v[166:169], v[218:221], v[86:89]
	v_mfma_f32_16x16x32_bf16 v[82:85], v[174:177], v[218:221], v[82:85]
	v_mfma_f32_16x16x32_bf16 v[70:73], v[166:169], v[226:229], v[70:73]
	v_mfma_f32_16x16x32_bf16 v[66:69], v[174:177], v[226:229], v[66:69]
	s_setprio 0
	s_barrier
	s_add_i32 s42, s42, s24
	v_lshl_add_u64 v[140:141], s[18:19], 0, v[0:1]
	s_mov_b32 m0, s42
	ds_read_b128 v[188:191], v145 offset:16384
	ds_read_b128 v[192:195], v145 offset:17408
	ds_read_b128 v[196:199], v145 offset:18432
	ds_read_b128 v[200:203], v145 offset:19456
	ds_read_b128 v[204:207], v145 offset:20480
	ds_read_b128 v[218:221], v145 offset:21504
	ds_read_b128 v[222:225], v145 offset:22528
	ds_read_b128 v[226:229], v145 offset:23552
	global_load_lds_dwordx4 v[140:141], off
	s_add_i32 m0, s42, 0x2000
	s_add_u32 s56, s18, 0x80000
	v_lshl_add_u64 v[178:179], s[18:19], 0, v[130:131]
	s_addc_u32 s57, s19, 0
	s_add_i32 s3, s3, s24
	global_load_lds_dwordx4 v[178:179], off
	v_lshl_add_u64 v[180:181], s[56:57], 0, v[0:1]
	s_mov_b32 m0, s3
	v_lshl_add_u64 v[182:183], s[20:21], 0, v[132:133]
	global_load_lds_dwordx4 v[180:181], off
	v_lshl_add_u64 v[180:181], s[56:57], 0, v[130:131]
	s_add_i32 m0, s3, 0x2000
	s_nop 0
	global_load_lds_dwordx4 v[180:181], off
	v_lshl_add_u64 v[180:181], s[20:21], 0, v[134:135]
	s_mov_b32 m0, s25
	s_nop 0
	global_load_lds_dwordx4 v[180:181], off
	s_mov_b32 m0, s26
	s_nop 0
	global_load_lds_dwordx4 v[182:183], off
	s_waitcnt vmcnt(8)
	s_waitcnt lgkmcnt(0)
	v_mfma_f32_16x16x32_bf16 v[62:65], v[146:149], v[188:191], v[62:65]
	v_mfma_f32_16x16x32_bf16 v[58:61], v[154:157], v[188:191], v[58:61]
	s_barrier
	s_setprio 1
	v_mfma_f32_16x16x32_bf16 v[46:49], v[146:149], v[196:199], v[46:49]
	v_mfma_f32_16x16x32_bf16 v[42:45], v[154:157], v[196:199], v[42:45]
	v_mfma_f32_16x16x32_bf16 v[30:33], v[146:149], v[204:207], v[30:33]
	v_mfma_f32_16x16x32_bf16 v[26:29], v[154:157], v[204:207], v[26:29]
	v_mfma_f32_16x16x32_bf16 v[14:17], v[146:149], v[222:225], v[14:17]
	v_mfma_f32_16x16x32_bf16 v[10:13], v[154:157], v[222:225], v[10:13]
	v_mfma_f32_16x16x32_bf16 v[62:65], v[150:153], v[192:195], v[62:65]
	v_mfma_f32_16x16x32_bf16 v[58:61], v[158:161], v[192:195], v[58:61]
	v_mfma_f32_16x16x32_bf16 v[46:49], v[150:153], v[200:203], v[46:49]
	v_mfma_f32_16x16x32_bf16 v[42:45], v[158:161], v[200:203], v[42:45]
	v_mfma_f32_16x16x32_bf16 v[30:33], v[150:153], v[218:221], v[30:33]
	v_mfma_f32_16x16x32_bf16 v[26:29], v[158:161], v[218:221], v[26:29]
	v_mfma_f32_16x16x32_bf16 v[14:17], v[150:153], v[226:229], v[14:17]
	v_mfma_f32_16x16x32_bf16 v[10:13], v[158:161], v[226:229], v[10:13]
	s_setprio 0
	s_setprio 1
	v_mfma_f32_16x16x32_bf16 v[54:57], v[162:165], v[188:191], v[54:57]
	v_mfma_f32_16x16x32_bf16 v[50:53], v[170:173], v[188:191], v[50:53]
	v_mfma_f32_16x16x32_bf16 v[38:41], v[162:165], v[196:199], v[38:41]
	v_mfma_f32_16x16x32_bf16 v[34:37], v[170:173], v[196:199], v[34:37]
	v_mfma_f32_16x16x32_bf16 v[22:25], v[162:165], v[204:207], v[22:25]
	v_mfma_f32_16x16x32_bf16 v[18:21], v[170:173], v[204:207], v[18:21]
	v_mfma_f32_16x16x32_bf16 v[6:9], v[162:165], v[222:225], v[6:9]
	v_mfma_f32_16x16x32_bf16 v[2:5], v[170:173], v[222:225], v[2:5]
	v_mfma_f32_16x16x32_bf16 v[54:57], v[166:169], v[192:195], v[54:57]
	v_mfma_f32_16x16x32_bf16 v[50:53], v[174:177], v[192:195], v[50:53]
	v_mfma_f32_16x16x32_bf16 v[38:41], v[166:169], v[200:203], v[38:41]
	v_mfma_f32_16x16x32_bf16 v[34:37], v[174:177], v[200:203], v[34:37]
	v_mfma_f32_16x16x32_bf16 v[22:25], v[166:169], v[218:221], v[22:25]
	v_mfma_f32_16x16x32_bf16 v[18:21], v[174:177], v[218:221], v[18:21]
	v_mfma_f32_16x16x32_bf16 v[6:9], v[166:169], v[226:229], v[6:9]
	v_mfma_f32_16x16x32_bf16 v[2:5], v[174:177], v[226:229], v[2:5]
	s_setprio 0
	s_barrier
	s_add_i32 s3, 0, 0x18000
	s_add_i32 s42, 0, 0x1c000
	v_add_u32_e32 v158, s3, v143
	v_add_u32_e32 v174, s42, v143
	ds_read_b128 v[146:149], v158
	ds_read_b128 v[150:153], v158 offset:1024
	ds_read_b128 v[154:157], v158 offset:2048
	ds_read_b128 v[158:161], v158 offset:3072
	ds_read_b128 v[162:165], v174
	ds_read_b128 v[166:169], v174 offset:1024
	ds_read_b128 v[170:173], v174 offset:2048
	ds_read_b128 v[174:177], v174 offset:3072
	s_add_u32 s20, s20, 0x80000
	s_addc_u32 s21, s21, 0
	s_mov_b32 m0, s27
	v_lshl_add_u64 v[184:185], s[20:21], 0, v[134:135]
	ds_read_b128 v[188:191], v145 offset:32768
	ds_read_b128 v[192:195], v145 offset:33792
	ds_read_b128 v[196:199], v145 offset:34816
	ds_read_b128 v[200:203], v145 offset:35840
	ds_read_b128 v[204:207], v145 offset:36864
	ds_read_b128 v[218:221], v145 offset:37888
	ds_read_b128 v[222:225], v145 offset:38912
	ds_read_b128 v[226:229], v145 offset:39936
	global_load_lds_dwordx4 v[184:185], off
	v_lshl_add_u64 v[184:185], s[20:21], 0, v[132:133]
	s_mov_b32 m0, s28
	s_nop 0
	global_load_lds_dwordx4 v[184:185], off
	s_waitcnt vmcnt(8)
	s_waitcnt lgkmcnt(0)
	v_mfma_f32_16x16x32_bf16 v[126:129], v[146:149], v[188:191], v[126:129]
	v_mfma_f32_16x16x32_bf16 v[122:125], v[154:157], v[188:191], v[122:125]
	s_barrier
	s_setprio 1
	v_mfma_f32_16x16x32_bf16 v[110:113], v[146:149], v[196:199], v[110:113]
	v_mfma_f32_16x16x32_bf16 v[106:109], v[154:157], v[196:199], v[106:109]
	v_mfma_f32_16x16x32_bf16 v[94:97], v[146:149], v[204:207], v[94:97]
	v_mfma_f32_16x16x32_bf16 v[90:93], v[154:157], v[204:207], v[90:93]
	v_mfma_f32_16x16x32_bf16 v[78:81], v[146:149], v[222:225], v[78:81]
	v_mfma_f32_16x16x32_bf16 v[74:77], v[154:157], v[222:225], v[74:77]
	v_mfma_f32_16x16x32_bf16 v[126:129], v[150:153], v[192:195], v[126:129]
	v_mfma_f32_16x16x32_bf16 v[122:125], v[158:161], v[192:195], v[122:125]
	v_mfma_f32_16x16x32_bf16 v[110:113], v[150:153], v[200:203], v[110:113]
	v_mfma_f32_16x16x32_bf16 v[106:109], v[158:161], v[200:203], v[106:109]
	v_mfma_f32_16x16x32_bf16 v[94:97], v[150:153], v[218:221], v[94:97]
	v_mfma_f32_16x16x32_bf16 v[90:93], v[158:161], v[218:221], v[90:93]
	v_mfma_f32_16x16x32_bf16 v[78:81], v[150:153], v[226:229], v[78:81]
	v_mfma_f32_16x16x32_bf16 v[74:77], v[158:161], v[226:229], v[74:77]
	s_setprio 0
	s_setprio 1
	v_mfma_f32_16x16x32_bf16 v[118:121], v[162:165], v[188:191], v[118:121]
	v_mfma_f32_16x16x32_bf16 v[114:117], v[170:173], v[188:191], v[114:117]
	v_mfma_f32_16x16x32_bf16 v[102:105], v[162:165], v[196:199], v[102:105]
	v_mfma_f32_16x16x32_bf16 v[98:101], v[170:173], v[196:199], v[98:101]
	v_mfma_f32_16x16x32_bf16 v[86:89], v[162:165], v[204:207], v[86:89]
	v_mfma_f32_16x16x32_bf16 v[82:85], v[170:173], v[204:207], v[82:85]
	v_mfma_f32_16x16x32_bf16 v[70:73], v[162:165], v[222:225], v[70:73]
	v_mfma_f32_16x16x32_bf16 v[66:69], v[170:173], v[222:225], v[66:69]
	v_mfma_f32_16x16x32_bf16 v[118:121], v[166:169], v[192:195], v[118:121]
	v_mfma_f32_16x16x32_bf16 v[114:117], v[174:177], v[192:195], v[114:117]
	v_mfma_f32_16x16x32_bf16 v[102:105], v[166:169], v[200:203], v[102:105]
	v_mfma_f32_16x16x32_bf16 v[98:101], v[174:177], v[200:203], v[98:101]
	v_mfma_f32_16x16x32_bf16 v[86:89], v[166:169], v[218:221], v[86:89]
	v_mfma_f32_16x16x32_bf16 v[82:85], v[174:177], v[218:221], v[82:85]
	v_mfma_f32_16x16x32_bf16 v[70:73], v[166:169], v[226:229], v[70:73]
	v_mfma_f32_16x16x32_bf16 v[66:69], v[174:177], v[226:229], v[66:69]
	s_setprio 0
	s_barrier
	s_add_i32 s3, s3, s24
	v_lshl_add_u64 v[140:141], v[140:141], 0, s[52:53]
	s_mov_b32 m0, s3
	ds_read_b128 v[188:191], v145 offset:49152
	ds_read_b128 v[192:195], v145 offset:50176
	ds_read_b128 v[196:199], v145 offset:51200
	ds_read_b128 v[200:203], v145 offset:52224
	ds_read_b128 v[204:207], v145 offset:53248
	ds_read_b128 v[218:221], v145 offset:54272
	ds_read_b128 v[222:225], v145 offset:55296
	ds_read_b128 v[226:229], v145 offset:56320
	global_load_lds_dwordx4 v[140:141], off
	s_add_i32 m0, s3, 0x2000
	s_add_u32 s18, s18, 0x80080
	v_lshl_add_u64 v[140:141], v[178:179], 0, s[52:53]
	s_addc_u32 s19, s19, 0
	s_add_i32 s3, s42, s24
	global_load_lds_dwordx4 v[140:141], off
	v_lshl_add_u64 v[140:141], s[18:19], 0, v[0:1]
	s_mov_b32 m0, s3
	s_nop 0
	global_load_lds_dwordx4 v[140:141], off
	v_lshl_add_u64 v[140:141], s[18:19], 0, v[130:131]
	s_add_i32 m0, s3, 0x2000
	s_nop 0
	global_load_lds_dwordx4 v[140:141], off
	v_lshl_add_u64 v[140:141], v[180:181], 0, s[52:53]
	s_mov_b32 m0, s29
	s_nop 0
	global_load_lds_dwordx4 v[140:141], off
	v_lshl_add_u64 v[140:141], v[182:183], 0, s[52:53]
	s_mov_b32 m0, s30
	s_nop 0
	global_load_lds_dwordx4 v[140:141], off
	s_waitcnt vmcnt(8)
	s_waitcnt lgkmcnt(0)
	v_mfma_f32_16x16x32_bf16 v[62:65], v[146:149], v[188:191], v[62:65]
	v_mfma_f32_16x16x32_bf16 v[58:61], v[154:157], v[188:191], v[58:61]
	s_barrier
	s_setprio 1
	v_mfma_f32_16x16x32_bf16 v[46:49], v[146:149], v[196:199], v[46:49]
	v_mfma_f32_16x16x32_bf16 v[42:45], v[154:157], v[196:199], v[42:45]
	v_mfma_f32_16x16x32_bf16 v[30:33], v[146:149], v[204:207], v[30:33]
	v_mfma_f32_16x16x32_bf16 v[26:29], v[154:157], v[204:207], v[26:29]
	v_mfma_f32_16x16x32_bf16 v[14:17], v[146:149], v[222:225], v[14:17]
	v_mfma_f32_16x16x32_bf16 v[10:13], v[154:157], v[222:225], v[10:13]
	v_mfma_f32_16x16x32_bf16 v[62:65], v[150:153], v[192:195], v[62:65]
	v_mfma_f32_16x16x32_bf16 v[58:61], v[158:161], v[192:195], v[58:61]
	v_mfma_f32_16x16x32_bf16 v[46:49], v[150:153], v[200:203], v[46:49]
	v_mfma_f32_16x16x32_bf16 v[42:45], v[158:161], v[200:203], v[42:45]
	v_mfma_f32_16x16x32_bf16 v[30:33], v[150:153], v[218:221], v[30:33]
	v_mfma_f32_16x16x32_bf16 v[26:29], v[158:161], v[218:221], v[26:29]
	v_mfma_f32_16x16x32_bf16 v[14:17], v[150:153], v[226:229], v[14:17]
	v_mfma_f32_16x16x32_bf16 v[10:13], v[158:161], v[226:229], v[10:13]
	s_setprio 0
	s_setprio 1
	v_mfma_f32_16x16x32_bf16 v[54:57], v[162:165], v[188:191], v[54:57]
	v_mfma_f32_16x16x32_bf16 v[50:53], v[170:173], v[188:191], v[50:53]
	v_mfma_f32_16x16x32_bf16 v[38:41], v[162:165], v[196:199], v[38:41]
	v_mfma_f32_16x16x32_bf16 v[34:37], v[170:173], v[196:199], v[34:37]
	v_mfma_f32_16x16x32_bf16 v[22:25], v[162:165], v[204:207], v[22:25]
	v_mfma_f32_16x16x32_bf16 v[18:21], v[170:173], v[204:207], v[18:21]
	v_mfma_f32_16x16x32_bf16 v[6:9], v[162:165], v[222:225], v[6:9]
	v_mfma_f32_16x16x32_bf16 v[2:5], v[170:173], v[222:225], v[2:5]
	v_mfma_f32_16x16x32_bf16 v[54:57], v[166:169], v[192:195], v[54:57]
	v_mfma_f32_16x16x32_bf16 v[50:53], v[174:177], v[192:195], v[50:53]
	v_mfma_f32_16x16x32_bf16 v[38:41], v[166:169], v[200:203], v[38:41]
	v_mfma_f32_16x16x32_bf16 v[34:37], v[174:177], v[200:203], v[34:37]
	v_mfma_f32_16x16x32_bf16 v[22:25], v[166:169], v[218:221], v[22:25]
	v_mfma_f32_16x16x32_bf16 v[18:21], v[174:177], v[218:221], v[18:21]
	v_mfma_f32_16x16x32_bf16 v[6:9], v[166:169], v[226:229], v[6:9]
	v_mfma_f32_16x16x32_bf16 v[2:5], v[174:177], v[226:229], v[2:5]
	s_setprio 0
	s_barrier
	s_add_i32 s46, s46, 2
	s_add_u32 s16, s16, 0x100
	s_addc_u32 s17, s17, 0
	s_add_u32 s44, s44, 0x100
	s_addc_u32 s45, s45, 0
	s_cmp_gt_u32 s46, 29
	s_cbranch_scc0 .LBB0_959
	s_and_b64 vcc, exec, s[6:7]
	s_movk_i32 s40, 0x4000
	s_movk_i32 s41, 0x6000
	s_mov_b32 s44, 0x8000
	s_mov_b32 s45, 0xa000
	s_cbranch_vccz .LBB0_962
	s_barrier

.LBB0_1024:
	s_add_u32 s3, s20, 0xffe00080
	s_addc_u32 s22, s21, -1
	s_add_i32 s42, 0, 0x10000
	s_cmpk_eq_i32 s57, 0x7c
	s_cselect_b32 s25, s15, s22
	s_cselect_b32 s24, s45, s3
	s_cselect_b32 s23, s13, s56
	s_cselect_b32 s22, s46, s47
	s_add_i32 s3, 0, 0x14000
	v_add_u32_e32 v152, s42, v163
	v_add_u32_e32 v160, s3, v163
	ds_read_b128 v[140:143], v152
	ds_read_b128 v[144:147], v152 offset:1024
	ds_read_b128 v[148:151], v152 offset:2048
	ds_read_b128 v[152:155], v152 offset:3072
	ds_read_b128 v[156:159], v160
	ds_read_b128 v[166:169], v160 offset:1024
	ds_read_b128 v[170:173], v160 offset:2048
	ds_read_b128 v[174:177], v160 offset:3072
	v_lshl_add_u64 v[160:161], s[20:21], 0, v[136:137]
	s_add_i32 m0, s28, 0xc000
	ds_read_b128 v[188:191], v165
	ds_read_b128 v[192:195], v165 offset:1024
	ds_read_b128 v[196:199], v165 offset:2048
	ds_read_b128 v[200:203], v165 offset:3072
	ds_read_b128 v[204:207], v165 offset:4096
	ds_read_b128 v[218:221], v165 offset:5120
	ds_read_b128 v[222:225], v165 offset:6144
	ds_read_b128 v[226:229], v165 offset:7168
	global_load_lds_dwordx4 v[160:161], off
	v_lshl_add_u64 v[160:161], s[20:21], 0, v[138:139]
	s_add_i32 m0, s28, 0xe000
	s_nop 0
	global_load_lds_dwordx4 v[160:161], off
	s_waitcnt vmcnt(8)
	s_waitcnt lgkmcnt(0)
	v_mfma_f32_16x16x32_bf16 v[126:129], v[140:143], v[188:191], v[126:129]
	v_mfma_f32_16x16x32_bf16 v[122:125], v[148:151], v[188:191], v[122:125]
	s_barrier
	s_setprio 1
	v_mfma_f32_16x16x32_bf16 v[110:113], v[140:143], v[196:199], v[110:113]
	v_mfma_f32_16x16x32_bf16 v[106:109], v[148:151], v[196:199], v[106:109]
	v_mfma_f32_16x16x32_bf16 v[94:97], v[140:143], v[204:207], v[94:97]
	v_mfma_f32_16x16x32_bf16 v[90:93], v[148:151], v[204:207], v[90:93]
	v_mfma_f32_16x16x32_bf16 v[78:81], v[140:143], v[222:225], v[78:81]
	v_mfma_f32_16x16x32_bf16 v[74:77], v[148:151], v[222:225], v[74:77]
	v_mfma_f32_16x16x32_bf16 v[126:129], v[144:147], v[192:195], v[126:129]
	v_mfma_f32_16x16x32_bf16 v[122:125], v[152:155], v[192:195], v[122:125]
	v_mfma_f32_16x16x32_bf16 v[110:113], v[144:147], v[200:203], v[110:113]
	v_mfma_f32_16x16x32_bf16 v[106:109], v[152:155], v[200:203], v[106:109]
	v_mfma_f32_16x16x32_bf16 v[94:97], v[144:147], v[218:221], v[94:97]
	v_mfma_f32_16x16x32_bf16 v[90:93], v[152:155], v[218:221], v[90:93]
	v_mfma_f32_16x16x32_bf16 v[78:81], v[144:147], v[226:229], v[78:81]
	v_mfma_f32_16x16x32_bf16 v[74:77], v[152:155], v[226:229], v[74:77]
	s_setprio 0
	s_setprio 1
	v_mfma_f32_16x16x32_bf16 v[118:121], v[156:159], v[188:191], v[118:121]
	v_mfma_f32_16x16x32_bf16 v[114:117], v[170:173], v[188:191], v[114:117]
	v_mfma_f32_16x16x32_bf16 v[102:105], v[156:159], v[196:199], v[102:105]
	v_mfma_f32_16x16x32_bf16 v[98:101], v[170:173], v[196:199], v[98:101]
	v_mfma_f32_16x16x32_bf16 v[86:89], v[156:159], v[204:207], v[86:89]
	v_mfma_f32_16x16x32_bf16 v[82:85], v[170:173], v[204:207], v[82:85]
	v_mfma_f32_16x16x32_bf16 v[70:73], v[156:159], v[222:225], v[70:73]
	v_mfma_f32_16x16x32_bf16 v[66:69], v[170:173], v[222:225], v[66:69]
	v_mfma_f32_16x16x32_bf16 v[118:121], v[166:169], v[192:195], v[118:121]
	v_mfma_f32_16x16x32_bf16 v[114:117], v[174:177], v[192:195], v[114:117]
	v_mfma_f32_16x16x32_bf16 v[102:105], v[166:169], v[200:203], v[102:105]
	v_mfma_f32_16x16x32_bf16 v[98:101], v[174:177], v[200:203], v[98:101]
	v_mfma_f32_16x16x32_bf16 v[86:89], v[166:169], v[218:221], v[86:89]
	v_mfma_f32_16x16x32_bf16 v[82:85], v[174:177], v[218:221], v[82:85]
	v_mfma_f32_16x16x32_bf16 v[70:73], v[166:169], v[226:229], v[70:73]
	v_mfma_f32_16x16x32_bf16 v[66:69], v[174:177], v[226:229], v[66:69]
	s_setprio 0
	s_barrier
	s_add_i32 s42, s42, s27
	v_lshl_add_u64 v[160:161], s[22:23], 0, v[0:1]
	s_mov_b32 m0, s42
	ds_read_b128 v[188:191], v165 offset:16384
	ds_read_b128 v[192:195], v165 offset:17408
	ds_read_b128 v[196:199], v165 offset:18432
	ds_read_b128 v[200:203], v165 offset:19456
	ds_read_b128 v[204:207], v165 offset:20480
	ds_read_b128 v[218:221], v165 offset:21504
	ds_read_b128 v[222:225], v165 offset:22528
	ds_read_b128 v[226:229], v165 offset:23552
	global_load_lds_dwordx4 v[160:161], off
	s_add_i32 m0, s42, 0x2000
	s_add_u32 s58, s22, 0x200000
	v_lshl_add_u64 v[178:179], s[22:23], 0, v[130:131]
	s_addc_u32 s59, s23, 0
	s_add_i32 s3, s3, s27
	global_load_lds_dwordx4 v[178:179], off
	v_lshl_add_u64 v[180:181], s[58:59], 0, v[0:1]
	s_mov_b32 m0, s3
	v_lshl_add_u64 v[182:183], s[24:25], 0, v[132:133]
	global_load_lds_dwordx4 v[180:181], off
	v_lshl_add_u64 v[180:181], s[58:59], 0, v[130:131]
	s_add_i32 m0, s3, 0x2000
	s_nop 0
	global_load_lds_dwordx4 v[180:181], off
	v_lshl_add_u64 v[180:181], s[24:25], 0, v[134:135]
	s_mov_b32 m0, s28
	s_nop 0
	global_load_lds_dwordx4 v[180:181], off
	s_mov_b32 m0, s29
	s_nop 0
	global_load_lds_dwordx4 v[182:183], off
	s_waitcnt vmcnt(8)
	s_waitcnt lgkmcnt(0)
	v_mfma_f32_16x16x32_bf16 v[62:65], v[140:143], v[188:191], v[62:65]
	v_mfma_f32_16x16x32_bf16 v[58:61], v[148:151], v[188:191], v[58:61]
	s_barrier
	s_setprio 1
	v_mfma_f32_16x16x32_bf16 v[46:49], v[140:143], v[196:199], v[46:49]
	v_mfma_f32_16x16x32_bf16 v[42:45], v[148:151], v[196:199], v[42:45]
	v_mfma_f32_16x16x32_bf16 v[30:33], v[140:143], v[204:207], v[30:33]
	v_mfma_f32_16x16x32_bf16 v[26:29], v[148:151], v[204:207], v[26:29]
	v_mfma_f32_16x16x32_bf16 v[14:17], v[140:143], v[222:225], v[14:17]
	v_mfma_f32_16x16x32_bf16 v[10:13], v[148:151], v[222:225], v[10:13]
	v_mfma_f32_16x16x32_bf16 v[62:65], v[144:147], v[192:195], v[62:65]
	v_mfma_f32_16x16x32_bf16 v[58:61], v[152:155], v[192:195], v[58:61]
	v_mfma_f32_16x16x32_bf16 v[46:49], v[144:147], v[200:203], v[46:49]
	v_mfma_f32_16x16x32_bf16 v[42:45], v[152:155], v[200:203], v[42:45]
	v_mfma_f32_16x16x32_bf16 v[30:33], v[144:147], v[218:221], v[30:33]
	v_mfma_f32_16x16x32_bf16 v[26:29], v[152:155], v[218:221], v[26:29]
	v_mfma_f32_16x16x32_bf16 v[14:17], v[144:147], v[226:229], v[14:17]
	v_mfma_f32_16x16x32_bf16 v[10:13], v[152:155], v[226:229], v[10:13]
	s_setprio 0
	s_setprio 1
	v_mfma_f32_16x16x32_bf16 v[54:57], v[156:159], v[188:191], v[54:57]
	v_mfma_f32_16x16x32_bf16 v[50:53], v[170:173], v[188:191], v[50:53]
	v_mfma_f32_16x16x32_bf16 v[38:41], v[156:159], v[196:199], v[38:41]
	v_mfma_f32_16x16x32_bf16 v[34:37], v[170:173], v[196:199], v[34:37]
	v_mfma_f32_16x16x32_bf16 v[22:25], v[156:159], v[204:207], v[22:25]
	v_mfma_f32_16x16x32_bf16 v[18:21], v[170:173], v[204:207], v[18:21]
	v_mfma_f32_16x16x32_bf16 v[6:9], v[156:159], v[222:225], v[6:9]
	v_mfma_f32_16x16x32_bf16 v[2:5], v[170:173], v[222:225], v[2:5]
	v_mfma_f32_16x16x32_bf16 v[54:57], v[166:169], v[192:195], v[54:57]
	v_mfma_f32_16x16x32_bf16 v[50:53], v[174:177], v[192:195], v[50:53]
	v_mfma_f32_16x16x32_bf16 v[38:41], v[166:169], v[200:203], v[38:41]
	v_mfma_f32_16x16x32_bf16 v[34:37], v[174:177], v[200:203], v[34:37]
	v_mfma_f32_16x16x32_bf16 v[22:25], v[166:169], v[218:221], v[22:25]
	v_mfma_f32_16x16x32_bf16 v[18:21], v[174:177], v[218:221], v[18:21]
	v_mfma_f32_16x16x32_bf16 v[6:9], v[166:169], v[226:229], v[6:9]
	v_mfma_f32_16x16x32_bf16 v[2:5], v[174:177], v[226:229], v[2:5]
	s_setprio 0
	s_barrier
	s_add_i32 s3, 0, 0x18000
	s_add_i32 s42, 0, 0x1c000
	v_add_u32_e32 v152, s3, v163
	v_add_u32_e32 v174, s42, v163
	ds_read_b128 v[140:143], v152
	ds_read_b128 v[144:147], v152 offset:1024
	ds_read_b128 v[148:151], v152 offset:2048
	ds_read_b128 v[152:155], v152 offset:3072
	ds_read_b128 v[156:159], v174
	ds_read_b128 v[166:169], v174 offset:1024
	ds_read_b128 v[170:173], v174 offset:2048
	ds_read_b128 v[174:177], v174 offset:3072
	s_add_u32 s24, s24, 0x200000
	s_addc_u32 s25, s25, 0
	s_mov_b32 m0, s30
	v_lshl_add_u64 v[184:185], s[24:25], 0, v[134:135]
	ds_read_b128 v[188:191], v165 offset:32768
	ds_read_b128 v[192:195], v165 offset:33792
	ds_read_b128 v[196:199], v165 offset:34816
	ds_read_b128 v[200:203], v165 offset:35840
	ds_read_b128 v[204:207], v165 offset:36864
	ds_read_b128 v[218:221], v165 offset:37888
	ds_read_b128 v[222:225], v165 offset:38912
	ds_read_b128 v[226:229], v165 offset:39936
	global_load_lds_dwordx4 v[184:185], off
	v_lshl_add_u64 v[184:185], s[24:25], 0, v[132:133]
	s_mov_b32 m0, s31
	s_nop 0
	global_load_lds_dwordx4 v[184:185], off
	s_waitcnt vmcnt(8)
	s_waitcnt lgkmcnt(0)
	v_mfma_f32_16x16x32_bf16 v[126:129], v[140:143], v[188:191], v[126:129]
	v_mfma_f32_16x16x32_bf16 v[122:125], v[148:151], v[188:191], v[122:125]
	s_barrier
	s_setprio 1
	v_mfma_f32_16x16x32_bf16 v[110:113], v[140:143], v[196:199], v[110:113]
	v_mfma_f32_16x16x32_bf16 v[106:109], v[148:151], v[196:199], v[106:109]
	v_mfma_f32_16x16x32_bf16 v[94:97], v[140:143], v[204:207], v[94:97]
	v_mfma_f32_16x16x32_bf16 v[90:93], v[148:151], v[204:207], v[90:93]
	v_mfma_f32_16x16x32_bf16 v[78:81], v[140:143], v[222:225], v[78:81]
	v_mfma_f32_16x16x32_bf16 v[74:77], v[148:151], v[222:225], v[74:77]
	v_mfma_f32_16x16x32_bf16 v[126:129], v[144:147], v[192:195], v[126:129]
	v_mfma_f32_16x16x32_bf16 v[122:125], v[152:155], v[192:195], v[122:125]
	v_mfma_f32_16x16x32_bf16 v[110:113], v[144:147], v[200:203], v[110:113]
	v_mfma_f32_16x16x32_bf16 v[106:109], v[152:155], v[200:203], v[106:109]
	v_mfma_f32_16x16x32_bf16 v[94:97], v[144:147], v[218:221], v[94:97]
	v_mfma_f32_16x16x32_bf16 v[90:93], v[152:155], v[218:221], v[90:93]
	v_mfma_f32_16x16x32_bf16 v[78:81], v[144:147], v[226:229], v[78:81]
	v_mfma_f32_16x16x32_bf16 v[74:77], v[152:155], v[226:229], v[74:77]
	s_setprio 0
	s_setprio 1
	v_mfma_f32_16x16x32_bf16 v[118:121], v[156:159], v[188:191], v[118:121]
	v_mfma_f32_16x16x32_bf16 v[114:117], v[170:173], v[188:191], v[114:117]
	v_mfma_f32_16x16x32_bf16 v[102:105], v[156:159], v[196:199], v[102:105]
	v_mfma_f32_16x16x32_bf16 v[98:101], v[170:173], v[196:199], v[98:101]
	v_mfma_f32_16x16x32_bf16 v[86:89], v[156:159], v[204:207], v[86:89]
	v_mfma_f32_16x16x32_bf16 v[82:85], v[170:173], v[204:207], v[82:85]
	v_mfma_f32_16x16x32_bf16 v[70:73], v[156:159], v[222:225], v[70:73]
	v_mfma_f32_16x16x32_bf16 v[66:69], v[170:173], v[222:225], v[66:69]
	v_mfma_f32_16x16x32_bf16 v[118:121], v[166:169], v[192:195], v[118:121]
	v_mfma_f32_16x16x32_bf16 v[114:117], v[174:177], v[192:195], v[114:117]
	v_mfma_f32_16x16x32_bf16 v[102:105], v[166:169], v[200:203], v[102:105]
	v_mfma_f32_16x16x32_bf16 v[98:101], v[174:177], v[200:203], v[98:101]
	v_mfma_f32_16x16x32_bf16 v[86:89], v[166:169], v[218:221], v[86:89]
	v_mfma_f32_16x16x32_bf16 v[82:85], v[174:177], v[218:221], v[82:85]
	v_mfma_f32_16x16x32_bf16 v[70:73], v[166:169], v[226:229], v[70:73]
	v_mfma_f32_16x16x32_bf16 v[66:69], v[174:177], v[226:229], v[66:69]
	s_setprio 0
	s_barrier
	s_add_i32 s3, s3, s27
	v_lshl_add_u64 v[160:161], v[160:161], 0, s[52:53]
	s_mov_b32 m0, s3
	ds_read_b128 v[188:191], v165 offset:49152
	ds_read_b128 v[192:195], v165 offset:50176
	ds_read_b128 v[196:199], v165 offset:51200
	ds_read_b128 v[200:203], v165 offset:52224
	ds_read_b128 v[204:207], v165 offset:53248
	ds_read_b128 v[218:221], v165 offset:54272
	ds_read_b128 v[222:225], v165 offset:55296
	ds_read_b128 v[226:229], v165 offset:56320
	global_load_lds_dwordx4 v[160:161], off
	s_add_i32 m0, s3, 0x2000
	s_add_u32 s22, s22, 0x200080
	v_lshl_add_u64 v[160:161], v[178:179], 0, s[52:53]
	s_addc_u32 s23, s23, 0
	s_add_i32 s3, s42, s27
	global_load_lds_dwordx4 v[160:161], off
	v_lshl_add_u64 v[160:161], s[22:23], 0, v[0:1]
	s_mov_b32 m0, s3
	s_nop 0
	global_load_lds_dwordx4 v[160:161], off
	v_lshl_add_u64 v[160:161], s[22:23], 0, v[130:131]
	s_add_i32 m0, s3, 0x2000
	s_nop 0
	global_load_lds_dwordx4 v[160:161], off
	v_lshl_add_u64 v[160:161], v[180:181], 0, s[52:53]
	s_mov_b32 m0, s34
	s_nop 0
	global_load_lds_dwordx4 v[160:161], off
	v_lshl_add_u64 v[160:161], v[182:183], 0, s[52:53]
	s_mov_b32 m0, s35
	s_nop 0
	global_load_lds_dwordx4 v[160:161], off
	s_waitcnt vmcnt(8)
	s_waitcnt lgkmcnt(0)
	v_mfma_f32_16x16x32_bf16 v[62:65], v[140:143], v[188:191], v[62:65]
	v_mfma_f32_16x16x32_bf16 v[58:61], v[148:151], v[188:191], v[58:61]
	s_barrier
	s_setprio 1
	v_mfma_f32_16x16x32_bf16 v[46:49], v[140:143], v[196:199], v[46:49]
	v_mfma_f32_16x16x32_bf16 v[42:45], v[148:151], v[196:199], v[42:45]
	v_mfma_f32_16x16x32_bf16 v[30:33], v[140:143], v[204:207], v[30:33]
	v_mfma_f32_16x16x32_bf16 v[26:29], v[148:151], v[204:207], v[26:29]
	v_mfma_f32_16x16x32_bf16 v[14:17], v[140:143], v[222:225], v[14:17]
	v_mfma_f32_16x16x32_bf16 v[10:13], v[148:151], v[222:225], v[10:13]
	v_mfma_f32_16x16x32_bf16 v[62:65], v[144:147], v[192:195], v[62:65]
	v_mfma_f32_16x16x32_bf16 v[58:61], v[152:155], v[192:195], v[58:61]
	v_mfma_f32_16x16x32_bf16 v[46:49], v[144:147], v[200:203], v[46:49]
	v_mfma_f32_16x16x32_bf16 v[42:45], v[152:155], v[200:203], v[42:45]
	v_mfma_f32_16x16x32_bf16 v[30:33], v[144:147], v[218:221], v[30:33]
	v_mfma_f32_16x16x32_bf16 v[26:29], v[152:155], v[218:221], v[26:29]
	v_mfma_f32_16x16x32_bf16 v[14:17], v[144:147], v[226:229], v[14:17]
	v_mfma_f32_16x16x32_bf16 v[10:13], v[152:155], v[226:229], v[10:13]
	s_setprio 0
	s_setprio 1
	v_mfma_f32_16x16x32_bf16 v[54:57], v[156:159], v[188:191], v[54:57]
	v_mfma_f32_16x16x32_bf16 v[50:53], v[170:173], v[188:191], v[50:53]
	v_mfma_f32_16x16x32_bf16 v[38:41], v[156:159], v[196:199], v[38:41]
	v_mfma_f32_16x16x32_bf16 v[34:37], v[170:173], v[196:199], v[34:37]
	v_mfma_f32_16x16x32_bf16 v[22:25], v[156:159], v[204:207], v[22:25]
	v_mfma_f32_16x16x32_bf16 v[18:21], v[170:173], v[204:207], v[18:21]
	v_mfma_f32_16x16x32_bf16 v[6:9], v[156:159], v[222:225], v[6:9]
	v_mfma_f32_16x16x32_bf16 v[2:5], v[170:173], v[222:225], v[2:5]
	v_mfma_f32_16x16x32_bf16 v[54:57], v[166:169], v[192:195], v[54:57]
	v_mfma_f32_16x16x32_bf16 v[50:53], v[174:177], v[192:195], v[50:53]
	v_mfma_f32_16x16x32_bf16 v[38:41], v[166:169], v[200:203], v[38:41]
	v_mfma_f32_16x16x32_bf16 v[34:37], v[174:177], v[200:203], v[34:37]
	v_mfma_f32_16x16x32_bf16 v[22:25], v[166:169], v[218:221], v[22:25]
	v_mfma_f32_16x16x32_bf16 v[18:21], v[174:177], v[218:221], v[18:21]
	v_mfma_f32_16x16x32_bf16 v[6:9], v[166:169], v[226:229], v[6:9]
	v_mfma_f32_16x16x32_bf16 v[2:5], v[174:177], v[226:229], v[2:5]
	s_setprio 0
	s_barrier
	s_add_i32 s57, s57, 2
	s_add_u32 s20, s20, 0x100
	s_addc_u32 s21, s21, 0
	s_add_u32 s47, s47, 0x100
	s_addc_u32 s56, s56, 0
	s_cmpk_gt_u32 s57, 0x7d
	s_cbranch_scc0 .LBB0_1024
	s_and_b64 vcc, exec, s[10:11]
	s_mov_b32 s45, 0xa000
	s_cbranch_vccz .LBB0_1027
	s_barrier

.LBB0_1046:
	s_add_u32 s3, s18, 0xffe00080
	s_addc_u32 s20, s19, -1
	s_add_i32 s42, 0, 0x10000
	s_cmpk_eq_i32 s47, 0x7c
	s_cselect_b32 s23, s13, s20
	s_cselect_b32 s22, s41, s3
	s_cselect_b32 s21, s11, s46
	s_cselect_b32 s20, s44, s45
	s_add_i32 s3, 0, 0x14000
	v_add_u32_e32 v152, s42, v163
	v_add_u32_e32 v160, s3, v163
	ds_read_b128 v[140:143], v152
	ds_read_b128 v[144:147], v152 offset:1024
	ds_read_b128 v[148:151], v152 offset:2048
	ds_read_b128 v[152:155], v152 offset:3072
	ds_read_b128 v[156:159], v160
	ds_read_b128 v[166:169], v160 offset:1024
	ds_read_b128 v[170:173], v160 offset:2048
	ds_read_b128 v[174:177], v160 offset:3072
	v_lshl_add_u64 v[160:161], s[18:19], 0, v[136:137]
	s_add_i32 m0, s25, 0xc000
	ds_read_b128 v[188:191], v165
	ds_read_b128 v[192:195], v165 offset:1024
	ds_read_b128 v[196:199], v165 offset:2048
	ds_read_b128 v[200:203], v165 offset:3072
	ds_read_b128 v[204:207], v165 offset:4096
	ds_read_b128 v[218:221], v165 offset:5120
	ds_read_b128 v[222:225], v165 offset:6144
	ds_read_b128 v[226:229], v165 offset:7168
	global_load_lds_dwordx4 v[160:161], off
	v_lshl_add_u64 v[160:161], s[18:19], 0, v[138:139]
	s_add_i32 m0, s25, 0xe000
	s_nop 0
	global_load_lds_dwordx4 v[160:161], off
	s_waitcnt vmcnt(8)
	s_waitcnt lgkmcnt(0)
	v_mfma_f32_16x16x32_bf16 v[126:129], v[140:143], v[188:191], v[126:129]
	v_mfma_f32_16x16x32_bf16 v[122:125], v[148:151], v[188:191], v[122:125]
	s_barrier
	s_setprio 1
	v_mfma_f32_16x16x32_bf16 v[110:113], v[140:143], v[196:199], v[110:113]
	v_mfma_f32_16x16x32_bf16 v[106:109], v[148:151], v[196:199], v[106:109]
	v_mfma_f32_16x16x32_bf16 v[94:97], v[140:143], v[204:207], v[94:97]
	v_mfma_f32_16x16x32_bf16 v[90:93], v[148:151], v[204:207], v[90:93]
	v_mfma_f32_16x16x32_bf16 v[78:81], v[140:143], v[222:225], v[78:81]
	v_mfma_f32_16x16x32_bf16 v[74:77], v[148:151], v[222:225], v[74:77]
	v_mfma_f32_16x16x32_bf16 v[126:129], v[144:147], v[192:195], v[126:129]
	v_mfma_f32_16x16x32_bf16 v[122:125], v[152:155], v[192:195], v[122:125]
	v_mfma_f32_16x16x32_bf16 v[110:113], v[144:147], v[200:203], v[110:113]
	v_mfma_f32_16x16x32_bf16 v[106:109], v[152:155], v[200:203], v[106:109]
	v_mfma_f32_16x16x32_bf16 v[94:97], v[144:147], v[218:221], v[94:97]
	v_mfma_f32_16x16x32_bf16 v[90:93], v[152:155], v[218:221], v[90:93]
	v_mfma_f32_16x16x32_bf16 v[78:81], v[144:147], v[226:229], v[78:81]
	v_mfma_f32_16x16x32_bf16 v[74:77], v[152:155], v[226:229], v[74:77]
	s_setprio 0
	s_setprio 1
	v_mfma_f32_16x16x32_bf16 v[118:121], v[156:159], v[188:191], v[118:121]
	v_mfma_f32_16x16x32_bf16 v[114:117], v[170:173], v[188:191], v[114:117]
	v_mfma_f32_16x16x32_bf16 v[102:105], v[156:159], v[196:199], v[102:105]
	v_mfma_f32_16x16x32_bf16 v[98:101], v[170:173], v[196:199], v[98:101]
	v_mfma_f32_16x16x32_bf16 v[86:89], v[156:159], v[204:207], v[86:89]
	v_mfma_f32_16x16x32_bf16 v[82:85], v[170:173], v[204:207], v[82:85]
	v_mfma_f32_16x16x32_bf16 v[70:73], v[156:159], v[222:225], v[70:73]
	v_mfma_f32_16x16x32_bf16 v[66:69], v[170:173], v[222:225], v[66:69]
	v_mfma_f32_16x16x32_bf16 v[118:121], v[166:169], v[192:195], v[118:121]
	v_mfma_f32_16x16x32_bf16 v[114:117], v[174:177], v[192:195], v[114:117]
	v_mfma_f32_16x16x32_bf16 v[102:105], v[166:169], v[200:203], v[102:105]
	v_mfma_f32_16x16x32_bf16 v[98:101], v[174:177], v[200:203], v[98:101]
	v_mfma_f32_16x16x32_bf16 v[86:89], v[166:169], v[218:221], v[86:89]
	v_mfma_f32_16x16x32_bf16 v[82:85], v[174:177], v[218:221], v[82:85]
	v_mfma_f32_16x16x32_bf16 v[70:73], v[166:169], v[226:229], v[70:73]
	v_mfma_f32_16x16x32_bf16 v[66:69], v[174:177], v[226:229], v[66:69]
	s_setprio 0
	s_barrier
	s_add_i32 s42, s42, s24
	v_lshl_add_u64 v[160:161], s[20:21], 0, v[0:1]
	s_mov_b32 m0, s42
	ds_read_b128 v[188:191], v165 offset:16384
	ds_read_b128 v[192:195], v165 offset:17408
	ds_read_b128 v[196:199], v165 offset:18432
	ds_read_b128 v[200:203], v165 offset:19456
	ds_read_b128 v[204:207], v165 offset:20480
	ds_read_b128 v[218:221], v165 offset:21504
	ds_read_b128 v[222:225], v165 offset:22528
	ds_read_b128 v[226:229], v165 offset:23552
	global_load_lds_dwordx4 v[160:161], off
	s_add_i32 m0, s42, 0x2000
	s_add_u32 s56, s20, 0x200000
	v_lshl_add_u64 v[178:179], s[20:21], 0, v[130:131]
	s_addc_u32 s57, s21, 0
	s_add_i32 s3, s3, s24
	global_load_lds_dwordx4 v[178:179], off
	v_lshl_add_u64 v[180:181], s[56:57], 0, v[0:1]
	s_mov_b32 m0, s3
	v_lshl_add_u64 v[182:183], s[22:23], 0, v[132:133]
	global_load_lds_dwordx4 v[180:181], off
	v_lshl_add_u64 v[180:181], s[56:57], 0, v[130:131]
	s_add_i32 m0, s3, 0x2000
	s_nop 0
	global_load_lds_dwordx4 v[180:181], off
	v_lshl_add_u64 v[180:181], s[22:23], 0, v[134:135]
	s_mov_b32 m0, s25
	s_nop 0
	global_load_lds_dwordx4 v[180:181], off
	s_mov_b32 m0, s27
	s_nop 0
	global_load_lds_dwordx4 v[182:183], off
	s_waitcnt vmcnt(8)
	s_waitcnt lgkmcnt(0)
	v_mfma_f32_16x16x32_bf16 v[62:65], v[140:143], v[188:191], v[62:65]
	v_mfma_f32_16x16x32_bf16 v[58:61], v[148:151], v[188:191], v[58:61]
	s_barrier
	s_setprio 1
	v_mfma_f32_16x16x32_bf16 v[46:49], v[140:143], v[196:199], v[46:49]
	v_mfma_f32_16x16x32_bf16 v[42:45], v[148:151], v[196:199], v[42:45]
	v_mfma_f32_16x16x32_bf16 v[30:33], v[140:143], v[204:207], v[30:33]
	v_mfma_f32_16x16x32_bf16 v[26:29], v[148:151], v[204:207], v[26:29]
	v_mfma_f32_16x16x32_bf16 v[14:17], v[140:143], v[222:225], v[14:17]
	v_mfma_f32_16x16x32_bf16 v[10:13], v[148:151], v[222:225], v[10:13]
	v_mfma_f32_16x16x32_bf16 v[62:65], v[144:147], v[192:195], v[62:65]
	v_mfma_f32_16x16x32_bf16 v[58:61], v[152:155], v[192:195], v[58:61]
	v_mfma_f32_16x16x32_bf16 v[46:49], v[144:147], v[200:203], v[46:49]
	v_mfma_f32_16x16x32_bf16 v[42:45], v[152:155], v[200:203], v[42:45]
	v_mfma_f32_16x16x32_bf16 v[30:33], v[144:147], v[218:221], v[30:33]
	v_mfma_f32_16x16x32_bf16 v[26:29], v[152:155], v[218:221], v[26:29]
	v_mfma_f32_16x16x32_bf16 v[14:17], v[144:147], v[226:229], v[14:17]
	v_mfma_f32_16x16x32_bf16 v[10:13], v[152:155], v[226:229], v[10:13]
	s_setprio 0
	s_setprio 1
	v_mfma_f32_16x16x32_bf16 v[54:57], v[156:159], v[188:191], v[54:57]
	v_mfma_f32_16x16x32_bf16 v[50:53], v[170:173], v[188:191], v[50:53]
	v_mfma_f32_16x16x32_bf16 v[38:41], v[156:159], v[196:199], v[38:41]
	v_mfma_f32_16x16x32_bf16 v[34:37], v[170:173], v[196:199], v[34:37]
	v_mfma_f32_16x16x32_bf16 v[22:25], v[156:159], v[204:207], v[22:25]
	v_mfma_f32_16x16x32_bf16 v[18:21], v[170:173], v[204:207], v[18:21]
	v_mfma_f32_16x16x32_bf16 v[6:9], v[156:159], v[222:225], v[6:9]
	v_mfma_f32_16x16x32_bf16 v[2:5], v[170:173], v[222:225], v[2:5]
	v_mfma_f32_16x16x32_bf16 v[54:57], v[166:169], v[192:195], v[54:57]
	v_mfma_f32_16x16x32_bf16 v[50:53], v[174:177], v[192:195], v[50:53]
	v_mfma_f32_16x16x32_bf16 v[38:41], v[166:169], v[200:203], v[38:41]
	v_mfma_f32_16x16x32_bf16 v[34:37], v[174:177], v[200:203], v[34:37]
	v_mfma_f32_16x16x32_bf16 v[22:25], v[166:169], v[218:221], v[22:25]
	v_mfma_f32_16x16x32_bf16 v[18:21], v[174:177], v[218:221], v[18:21]
	v_mfma_f32_16x16x32_bf16 v[6:9], v[166:169], v[226:229], v[6:9]
	v_mfma_f32_16x16x32_bf16 v[2:5], v[174:177], v[226:229], v[2:5]
	s_setprio 0
	s_barrier
	s_add_i32 s3, 0, 0x18000
	s_add_i32 s42, 0, 0x1c000
	v_add_u32_e32 v152, s3, v163
	v_add_u32_e32 v174, s42, v163
	ds_read_b128 v[140:143], v152
	ds_read_b128 v[144:147], v152 offset:1024
	ds_read_b128 v[148:151], v152 offset:2048
	ds_read_b128 v[152:155], v152 offset:3072
	ds_read_b128 v[156:159], v174
	ds_read_b128 v[166:169], v174 offset:1024
	ds_read_b128 v[170:173], v174 offset:2048
	ds_read_b128 v[174:177], v174 offset:3072
	s_add_u32 s22, s22, 0x200000
	s_addc_u32 s23, s23, 0
	s_mov_b32 m0, s28
	v_lshl_add_u64 v[184:185], s[22:23], 0, v[134:135]
	ds_read_b128 v[188:191], v165 offset:32768
	ds_read_b128 v[192:195], v165 offset:33792
	ds_read_b128 v[196:199], v165 offset:34816
	ds_read_b128 v[200:203], v165 offset:35840
	ds_read_b128 v[204:207], v165 offset:36864
	ds_read_b128 v[218:221], v165 offset:37888
	ds_read_b128 v[222:225], v165 offset:38912
	ds_read_b128 v[226:229], v165 offset:39936
	global_load_lds_dwordx4 v[184:185], off
	v_lshl_add_u64 v[184:185], s[22:23], 0, v[132:133]
	s_mov_b32 m0, s29
	s_nop 0
	global_load_lds_dwordx4 v[184:185], off
	s_waitcnt vmcnt(8)
	s_waitcnt lgkmcnt(0)
	v_mfma_f32_16x16x32_bf16 v[126:129], v[140:143], v[188:191], v[126:129]
	v_mfma_f32_16x16x32_bf16 v[122:125], v[148:151], v[188:191], v[122:125]
	s_barrier
	s_setprio 1
	v_mfma_f32_16x16x32_bf16 v[110:113], v[140:143], v[196:199], v[110:113]
	v_mfma_f32_16x16x32_bf16 v[106:109], v[148:151], v[196:199], v[106:109]
	v_mfma_f32_16x16x32_bf16 v[94:97], v[140:143], v[204:207], v[94:97]
	v_mfma_f32_16x16x32_bf16 v[90:93], v[148:151], v[204:207], v[90:93]
	v_mfma_f32_16x16x32_bf16 v[78:81], v[140:143], v[222:225], v[78:81]
	v_mfma_f32_16x16x32_bf16 v[74:77], v[148:151], v[222:225], v[74:77]
	v_mfma_f32_16x16x32_bf16 v[126:129], v[144:147], v[192:195], v[126:129]
	v_mfma_f32_16x16x32_bf16 v[122:125], v[152:155], v[192:195], v[122:125]
	v_mfma_f32_16x16x32_bf16 v[110:113], v[144:147], v[200:203], v[110:113]
	v_mfma_f32_16x16x32_bf16 v[106:109], v[152:155], v[200:203], v[106:109]
	v_mfma_f32_16x16x32_bf16 v[94:97], v[144:147], v[218:221], v[94:97]
	v_mfma_f32_16x16x32_bf16 v[90:93], v[152:155], v[218:221], v[90:93]
	v_mfma_f32_16x16x32_bf16 v[78:81], v[144:147], v[226:229], v[78:81]
	v_mfma_f32_16x16x32_bf16 v[74:77], v[152:155], v[226:229], v[74:77]
	s_setprio 0
	s_setprio 1
	v_mfma_f32_16x16x32_bf16 v[118:121], v[156:159], v[188:191], v[118:121]
	v_mfma_f32_16x16x32_bf16 v[114:117], v[170:173], v[188:191], v[114:117]
	v_mfma_f32_16x16x32_bf16 v[102:105], v[156:159], v[196:199], v[102:105]
	v_mfma_f32_16x16x32_bf16 v[98:101], v[170:173], v[196:199], v[98:101]
	v_mfma_f32_16x16x32_bf16 v[86:89], v[156:159], v[204:207], v[86:89]
	v_mfma_f32_16x16x32_bf16 v[82:85], v[170:173], v[204:207], v[82:85]
	v_mfma_f32_16x16x32_bf16 v[70:73], v[156:159], v[222:225], v[70:73]
	v_mfma_f32_16x16x32_bf16 v[66:69], v[170:173], v[222:225], v[66:69]
	v_mfma_f32_16x16x32_bf16 v[118:121], v[166:169], v[192:195], v[118:121]
	v_mfma_f32_16x16x32_bf16 v[114:117], v[174:177], v[192:195], v[114:117]
	v_mfma_f32_16x16x32_bf16 v[102:105], v[166:169], v[200:203], v[102:105]
	v_mfma_f32_16x16x32_bf16 v[98:101], v[174:177], v[200:203], v[98:101]
	v_mfma_f32_16x16x32_bf16 v[86:89], v[166:169], v[218:221], v[86:89]
	v_mfma_f32_16x16x32_bf16 v[82:85], v[174:177], v[218:221], v[82:85]
	v_mfma_f32_16x16x32_bf16 v[70:73], v[166:169], v[226:229], v[70:73]
	v_mfma_f32_16x16x32_bf16 v[66:69], v[174:177], v[226:229], v[66:69]
	s_setprio 0
	s_barrier
	s_add_i32 s3, s3, s24
	v_lshl_add_u64 v[160:161], v[160:161], 0, s[52:53]
	s_mov_b32 m0, s3
	ds_read_b128 v[188:191], v165 offset:49152
	ds_read_b128 v[192:195], v165 offset:50176
	ds_read_b128 v[196:199], v165 offset:51200
	ds_read_b128 v[200:203], v165 offset:52224
	ds_read_b128 v[204:207], v165 offset:53248
	ds_read_b128 v[218:221], v165 offset:54272
	ds_read_b128 v[222:225], v165 offset:55296
	ds_read_b128 v[226:229], v165 offset:56320
	global_load_lds_dwordx4 v[160:161], off
	s_add_i32 m0, s3, 0x2000
	s_add_u32 s20, s20, 0x200080
	v_lshl_add_u64 v[160:161], v[178:179], 0, s[52:53]
	s_addc_u32 s21, s21, 0
	s_add_i32 s3, s42, s24
	global_load_lds_dwordx4 v[160:161], off
	v_lshl_add_u64 v[160:161], s[20:21], 0, v[0:1]
	s_mov_b32 m0, s3
	s_nop 0
	global_load_lds_dwordx4 v[160:161], off
	v_lshl_add_u64 v[160:161], s[20:21], 0, v[130:131]
	s_add_i32 m0, s3, 0x2000
	s_nop 0
	global_load_lds_dwordx4 v[160:161], off
	v_lshl_add_u64 v[160:161], v[180:181], 0, s[52:53]
	s_mov_b32 m0, s30
	s_nop 0
	global_load_lds_dwordx4 v[160:161], off
	v_lshl_add_u64 v[160:161], v[182:183], 0, s[52:53]
	s_mov_b32 m0, s31
	s_nop 0
	global_load_lds_dwordx4 v[160:161], off
	s_waitcnt vmcnt(8)
	s_waitcnt lgkmcnt(0)
	v_mfma_f32_16x16x32_bf16 v[62:65], v[140:143], v[188:191], v[62:65]
	v_mfma_f32_16x16x32_bf16 v[58:61], v[148:151], v[188:191], v[58:61]
	s_barrier
	s_setprio 1
	v_mfma_f32_16x16x32_bf16 v[46:49], v[140:143], v[196:199], v[46:49]
	v_mfma_f32_16x16x32_bf16 v[42:45], v[148:151], v[196:199], v[42:45]
	v_mfma_f32_16x16x32_bf16 v[30:33], v[140:143], v[204:207], v[30:33]
	v_mfma_f32_16x16x32_bf16 v[26:29], v[148:151], v[204:207], v[26:29]
	v_mfma_f32_16x16x32_bf16 v[14:17], v[140:143], v[222:225], v[14:17]
	v_mfma_f32_16x16x32_bf16 v[10:13], v[148:151], v[222:225], v[10:13]
	v_mfma_f32_16x16x32_bf16 v[62:65], v[144:147], v[192:195], v[62:65]
	v_mfma_f32_16x16x32_bf16 v[58:61], v[152:155], v[192:195], v[58:61]
	v_mfma_f32_16x16x32_bf16 v[46:49], v[144:147], v[200:203], v[46:49]
	v_mfma_f32_16x16x32_bf16 v[42:45], v[152:155], v[200:203], v[42:45]
	v_mfma_f32_16x16x32_bf16 v[30:33], v[144:147], v[218:221], v[30:33]
	v_mfma_f32_16x16x32_bf16 v[26:29], v[152:155], v[218:221], v[26:29]
	v_mfma_f32_16x16x32_bf16 v[14:17], v[144:147], v[226:229], v[14:17]
	v_mfma_f32_16x16x32_bf16 v[10:13], v[152:155], v[226:229], v[10:13]
	s_setprio 0
	s_setprio 1
	v_mfma_f32_16x16x32_bf16 v[54:57], v[156:159], v[188:191], v[54:57]
	v_mfma_f32_16x16x32_bf16 v[50:53], v[170:173], v[188:191], v[50:53]
	v_mfma_f32_16x16x32_bf16 v[38:41], v[156:159], v[196:199], v[38:41]
	v_mfma_f32_16x16x32_bf16 v[34:37], v[170:173], v[196:199], v[34:37]
	v_mfma_f32_16x16x32_bf16 v[22:25], v[156:159], v[204:207], v[22:25]
	v_mfma_f32_16x16x32_bf16 v[18:21], v[170:173], v[204:207], v[18:21]
	v_mfma_f32_16x16x32_bf16 v[6:9], v[156:159], v[222:225], v[6:9]
	v_mfma_f32_16x16x32_bf16 v[2:5], v[170:173], v[222:225], v[2:5]
	v_mfma_f32_16x16x32_bf16 v[54:57], v[166:169], v[192:195], v[54:57]
	v_mfma_f32_16x16x32_bf16 v[50:53], v[174:177], v[192:195], v[50:53]
	v_mfma_f32_16x16x32_bf16 v[38:41], v[166:169], v[200:203], v[38:41]
	v_mfma_f32_16x16x32_bf16 v[34:37], v[174:177], v[200:203], v[34:37]
	v_mfma_f32_16x16x32_bf16 v[22:25], v[166:169], v[218:221], v[22:25]
	v_mfma_f32_16x16x32_bf16 v[18:21], v[174:177], v[218:221], v[18:21]
	v_mfma_f32_16x16x32_bf16 v[6:9], v[166:169], v[226:229], v[6:9]
	v_mfma_f32_16x16x32_bf16 v[2:5], v[174:177], v[226:229], v[2:5]
	s_setprio 0
	s_barrier
	s_add_i32 s47, s47, 2
	s_add_u32 s18, s18, 0x100
	s_addc_u32 s19, s19, 0
	s_add_u32 s45, s45, 0x100
	s_addc_u32 s46, s46, 0
	s_cmpk_gt_u32 s47, 0x7d
	s_cbranch_scc0 .LBB0_1046
	s_and_b64 vcc, exec, s[8:9]
	s_movk_i32 s41, 0x6000
	s_mov_b32 s44, 0x8000
	s_mov_b32 s45, 0xa000
	s_cbranch_vccz .LBB0_1049
	s_barrier
